# EpiRes epilogue: rows processed in pairs, even row also prefetches the odd row's residual loads so it never waits for store acks (counted vmcnt)
# baseline (speedup 1.0000x reference)
; __device__ __forceinline__ float swz16(float v) { return __builtin_bit_cast(float, __builtin_amdgcn_ds_swizzle(__builtin_bit_cast(int, v), 0x401F)); }
;     __device__ __forceinline__ void operator()(const f32x4 (&acc)[2][2][4][2], const Unit& u, int wr, int wc, int fr, int fq) const {
;     ...
;         for (int ai = 0; ai < 2; ++ai)
; #pragma unroll
;             for (int m = 0; m < 4; ++m) {
;                 const int row = row0 + ai * 128 + m * 16; float sq = 0.f;
; #pragma unroll
;                 for (int bj = 0; bj < 2; ++bj) {
;                     const size_t off = (size_t)row * DM + col0 + bj * 128;
;                     const f32x4 r0 = *(const f32x4*)(res + off), r1 = *(const f32x4*)(res + off + 4);
;                     const f32x4 v0 = acc[ai][bj][m][0] + r0, v1 = acc[ai][bj][m][1] + r1;
;                     *(f32x4*)(out + off) = v0; *(f32x4*)(out + off + 4) = v1;
;                     u32x4 o; o.x = pack2(v0[0], v0[1]); o.y = pack2(v0[2], v0[3]); o.z = pack2(v1[0], v1[1]); o.w = pack2(v1[2], v1[3]);
;                     *(u32x4*)(hb + off) = o;
;                     sq += v0[0] * v0[0] + v0[1] * v0[1] + v0[2] * v0[2] + v0[3] * v0[3] + v1[0] * v1[0] + v1[1] * v1[1] + v1[2] * v1[2] + v1[3] * v1[3];
;                 }
;                 sq += swz16(sq); sq = sum32(sq);
;                 if (fq == 0) ss_out[(size_t)row * 32 + u.pn * 4 + wc] = sq;
;             }
.LBB0_540:
	s_or_b64 exec, exec, s[40:41]
	v_or_b32_e32 v96, 32, v146
	v_ashrrev_i32_e32 v97, 31, v96
	v_lshlrev_b64 v[98:99], 11, v[96:97]
	v_lshl_add_u64 v[106:107], v[98:99], 0, v[144:145]
	v_lshlrev_b64 v[108:109], 2, v[106:107]
	v_lshl_add_u64 v[110:111], s[16:17], 0, v[108:109]
	global_load_dwordx4 v[98:101], v[110:111], off
	global_load_dwordx4 v[102:105], v[110:111], off offset:16
	global_load_dwordx4 v[230:233], v[110:111], off offset:512
	global_load_dwordx4 v[234:237], v[110:111], off offset:528
	s_mov_b32 s100, 0x20000
	s_mov_b32 s101, 0
	v_lshl_add_u64 v[242:243], v[110:111], 0, s[100:101]
	global_load_dwordx4 v[222:225], v[242:243], off
	global_load_dwordx4 v[226:229], v[242:243], off offset:16
	global_load_dwordx4 v[238:241], v[242:243], off offset:512
	global_load_dwordx4 v[242:245], v[242:243], off offset:528
	v_lshl_add_u64 v[106:107], v[106:107], 1, s[14:15]
	v_lshl_add_u64 v[108:109], s[22:23], 0, v[108:109]
	s_waitcnt vmcnt(7)
	v_pk_add_f32 v[94:95], v[94:95], v[100:101]
	v_pk_add_f32 v[92:93], v[92:93], v[98:99]
	s_waitcnt vmcnt(6)
	v_pk_add_f32 v[90:91], v[90:91], v[104:105]
	v_pk_add_f32 v[88:89], v[88:89], v[102:103]
	v_cvt_pk_bf16_f32 v98, v92, v93
	v_cvt_pk_bf16_f32 v99, v94, v95
	v_cvt_pk_bf16_f32 v100, v88, v89
	v_cvt_pk_bf16_f32 v101, v90, v91
	global_store_dwordx4 v[108:109], v[92:95], off
	global_store_dwordx4 v[108:109], v[88:91], off offset:16
	global_store_dwordx4 v[106:107], v[98:101], off
	v_mul_f32_e32 v93, v93, v93
	v_fmac_f32_e32 v93, v92, v92
	v_fmac_f32_e32 v93, v94, v94
	v_fmac_f32_e32 v93, v95, v95
	v_fmac_f32_e32 v93, v88, v88
	v_fmac_f32_e32 v93, v89, v89
	v_fmac_f32_e32 v93, v90, v90
	v_fmac_f32_e32 v93, v91, v91
	s_waitcnt vmcnt(8)
	v_pk_add_f32 v[86:87], v[86:87], v[232:233]
	v_pk_add_f32 v[84:85], v[84:85], v[230:231]
	s_waitcnt vmcnt(7)
	v_pk_add_f32 v[82:83], v[82:83], v[236:237]
	v_pk_add_f32 v[80:81], v[80:81], v[234:235]
	global_store_dwordx4 v[108:109], v[84:87], off offset:512
	global_store_dwordx4 v[108:109], v[80:83], off offset:528
	v_cvt_pk_bf16_f32 v88, v84, v85
	v_mul_f32_e32 v85, v85, v85
	v_fmac_f32_e32 v85, v84, v84
	v_fmac_f32_e32 v85, v86, v86
	v_fmac_f32_e32 v85, v87, v87
	v_fmac_f32_e32 v85, v80, v80
	v_fmac_f32_e32 v85, v81, v81
	v_fmac_f32_e32 v85, v82, v82
	v_fmac_f32_e32 v85, v83, v83
	v_add_f32_e32 v84, v93, v85
	ds_swizzle_b32 v85, v84 offset:swizzle(SWAP,16)
	v_cvt_pk_bf16_f32 v90, v80, v81
	v_cvt_pk_bf16_f32 v89, v86, v87
	v_cvt_pk_bf16_f32 v91, v82, v83
	global_store_dwordx4 v[106:107], v[88:91], off offset:256
	s_waitcnt lgkmcnt(0)
	v_add_f32_e32 v80, v84, v85
	v_mov_b32_e32 v81, v80
	s_nop 1
	v_permlane32_swap_b32_e32 v80, v81
	s_and_saveexec_b64 s[40:41], s[8:9]
	s_cbranch_execz .LBB0_542
	v_add_f32_e32 v82, v80, v81
	v_lshlrev_b64 v[80:81], 7, v[96:97]
	v_lshl_add_u64 v[80:81], s[18:19], 0, v[80:81]
	v_lshl_add_u64 v[80:81], s[38:39], 2, v[80:81]
	s_lshl_b32 s24, s55, 2
	v_lshl_add_u64 v[80:81], v[80:81], 0, s[24:25]
	global_store_dword v[80:81], v82, off
.LBB0_542:
	s_or_b64 exec, exec, s[40:41]
	v_or_b32_e32 v80, 48, v146
	v_ashrrev_i32_e32 v81, 31, v80
	v_lshlrev_b64 v[82:83], 11, v[80:81]
	v_lshl_add_u64 v[90:91], v[82:83], 0, v[144:145]
	v_lshlrev_b64 v[92:93], 2, v[90:91]
	v_lshl_add_u64 v[94:95], s[16:17], 0, v[92:93]
	v_lshl_add_u64 v[90:91], v[90:91], 1, s[14:15]
	v_lshl_add_u64 v[92:93], s[22:23], 0, v[92:93]
	s_waitcnt vmcnt(9)
	v_pk_add_f32 v[78:79], v[78:79], v[224:225]
	v_pk_add_f32 v[76:77], v[76:77], v[222:223]
	s_waitcnt vmcnt(8)
	v_pk_add_f32 v[74:75], v[74:75], v[228:229]
	v_pk_add_f32 v[72:73], v[72:73], v[226:227]
	v_cvt_pk_bf16_f32 v82, v76, v77
	v_cvt_pk_bf16_f32 v83, v78, v79
	v_cvt_pk_bf16_f32 v84, v72, v73
	v_cvt_pk_bf16_f32 v85, v74, v75
	global_store_dwordx4 v[92:93], v[76:79], off
	global_store_dwordx4 v[92:93], v[72:75], off offset:16
	global_store_dwordx4 v[90:91], v[82:85], off
	v_mul_f32_e32 v77, v77, v77
	v_fmac_f32_e32 v77, v76, v76
	v_fmac_f32_e32 v77, v78, v78
	v_fmac_f32_e32 v77, v79, v79
	v_fmac_f32_e32 v77, v72, v72
	v_fmac_f32_e32 v77, v73, v73
	v_fmac_f32_e32 v77, v74, v74
	v_fmac_f32_e32 v77, v75, v75
	s_waitcnt vmcnt(10)
	v_pk_add_f32 v[70:71], v[70:71], v[240:241]
	v_pk_add_f32 v[68:69], v[68:69], v[238:239]
	s_waitcnt vmcnt(9)
	v_pk_add_f32 v[66:67], v[66:67], v[244:245]
	v_pk_add_f32 v[64:65], v[64:65], v[242:243]
	global_store_dwordx4 v[92:93], v[68:71], off offset:512
	global_store_dwordx4 v[92:93], v[64:67], off offset:528
	v_cvt_pk_bf16_f32 v72, v68, v69
	v_mul_f32_e32 v69, v69, v69
	v_fmac_f32_e32 v69, v68, v68
	v_fmac_f32_e32 v69, v70, v70
	v_fmac_f32_e32 v69, v71, v71
	v_fmac_f32_e32 v69, v64, v64
	v_fmac_f32_e32 v69, v65, v65
	v_fmac_f32_e32 v69, v66, v66
	v_fmac_f32_e32 v69, v67, v67
	v_add_f32_e32 v68, v77, v69
	ds_swizzle_b32 v69, v68 offset:swizzle(SWAP,16)
	v_cvt_pk_bf16_f32 v74, v64, v65
	v_cvt_pk_bf16_f32 v73, v70, v71
	v_cvt_pk_bf16_f32 v75, v66, v67
	global_store_dwordx4 v[90:91], v[72:75], off offset:256
	s_waitcnt lgkmcnt(0)
	v_add_f32_e32 v64, v68, v69
	v_mov_b32_e32 v65, v64
	s_nop 1
	v_permlane32_swap_b32_e32 v64, v65
	s_and_saveexec_b64 s[40:41], s[8:9]
	s_cbranch_execz .LBB0_544
	v_add_f32_e32 v66, v64, v65
	v_lshlrev_b64 v[64:65], 7, v[80:81]
	v_lshl_add_u64 v[64:65], s[18:19], 0, v[64:65]
	v_lshl_add_u64 v[64:65], s[38:39], 2, v[64:65]
	s_lshl_b32 s24, s55, 2
	v_lshl_add_u64 v[64:65], v[64:65], 0, s[24:25]
	global_store_dword v[64:65], v66, off
; __device__ __forceinline__ float swz16(float v) { return __builtin_bit_cast(float, __builtin_amdgcn_ds_swizzle(__builtin_bit_cast(int, v), 0x401F)); }
;     __device__ __forceinline__ void operator()(const f32x4 (&acc)[2][2][4][2], const Unit& u, int wr, int wc, int fr, int fq) const {
;     ...
;         for (int ai = 0; ai < 2; ++ai)
; #pragma unroll
;             for (int m = 0; m < 4; ++m) {
;                 const int row = row0 + ai * 128 + m * 16; float sq = 0.f;
; #pragma unroll
;                 for (int bj = 0; bj < 2; ++bj) {
;                     const size_t off = (size_t)row * DM + col0 + bj * 128;
;                     const f32x4 r0 = *(const f32x4*)(res + off), r1 = *(const f32x4*)(res + off + 4);
;                     const f32x4 v0 = acc[ai][bj][m][0] + r0, v1 = acc[ai][bj][m][1] + r1;
;                     *(f32x4*)(out + off) = v0; *(f32x4*)(out + off + 4) = v1;
;                     u32x4 o; o.x = pack2(v0[0], v0[1]); o.y = pack2(v0[2], v0[3]); o.z = pack2(v1[0], v1[1]); o.w = pack2(v1[2], v1[3]);
;                     *(u32x4*)(hb + off) = o;
;                     sq += v0[0] * v0[0] + v0[1] * v0[1] + v0[2] * v0[2] + v0[3] * v0[3] + v1[0] * v1[0] + v1[1] * v1[1] + v1[2] * v1[2] + v1[3] * v1[3];
;                 }
;                 sq += swz16(sq); sq = sum32(sq);
;                 if (fq == 0) ss_out[(size_t)row * 32 + u.pn * 4 + wc] = sq;
;             }
.LBB0_544:
	s_or_b64 exec, exec, s[40:41]
	v_add_u32_e32 v64, 0x80, v146
	v_ashrrev_i32_e32 v65, 31, v64
	v_lshlrev_b64 v[66:67], 11, v[64:65]
	v_lshl_add_u64 v[74:75], v[66:67], 0, v[144:145]
	v_lshlrev_b64 v[76:77], 2, v[74:75]
	v_lshl_add_u64 v[78:79], s[16:17], 0, v[76:77]
	global_load_dwordx4 v[66:69], v[78:79], off
	global_load_dwordx4 v[70:73], v[78:79], off offset:16
	global_load_dwordx4 v[230:233], v[78:79], off offset:512
	global_load_dwordx4 v[234:237], v[78:79], off offset:528
	s_mov_b32 s100, 0x20000
	s_mov_b32 s101, 0
	v_lshl_add_u64 v[242:243], v[78:79], 0, s[100:101]
	global_load_dwordx4 v[222:225], v[242:243], off
	global_load_dwordx4 v[226:229], v[242:243], off offset:16
	global_load_dwordx4 v[238:241], v[242:243], off offset:512
	global_load_dwordx4 v[242:245], v[242:243], off offset:528
	v_lshl_add_u64 v[74:75], v[74:75], 1, s[14:15]
	v_lshl_add_u64 v[76:77], s[22:23], 0, v[76:77]
	s_waitcnt vmcnt(7)
	v_pk_add_f32 v[62:63], v[62:63], v[68:69]
	v_pk_add_f32 v[60:61], v[60:61], v[66:67]
	s_waitcnt vmcnt(6)
	v_pk_add_f32 v[58:59], v[58:59], v[72:73]
	v_pk_add_f32 v[56:57], v[56:57], v[70:71]
	v_cvt_pk_bf16_f32 v66, v60, v61
	v_cvt_pk_bf16_f32 v67, v62, v63
	v_cvt_pk_bf16_f32 v68, v56, v57
	v_cvt_pk_bf16_f32 v69, v58, v59
	global_store_dwordx4 v[76:77], v[60:63], off
	global_store_dwordx4 v[76:77], v[56:59], off offset:16
	global_store_dwordx4 v[74:75], v[66:69], off
	v_mul_f32_e32 v61, v61, v61
	v_fmac_f32_e32 v61, v60, v60
	v_fmac_f32_e32 v61, v62, v62
	v_fmac_f32_e32 v61, v63, v63
	v_fmac_f32_e32 v61, v56, v56
	v_fmac_f32_e32 v61, v57, v57
	v_fmac_f32_e32 v61, v58, v58
	v_fmac_f32_e32 v61, v59, v59
	s_waitcnt vmcnt(8)
	v_pk_add_f32 v[54:55], v[54:55], v[232:233]
	v_pk_add_f32 v[52:53], v[52:53], v[230:231]
	s_waitcnt vmcnt(7)
	v_pk_add_f32 v[50:51], v[50:51], v[236:237]
	v_pk_add_f32 v[48:49], v[48:49], v[234:235]
	global_store_dwordx4 v[76:77], v[52:55], off offset:512
	global_store_dwordx4 v[76:77], v[48:51], off offset:528
	v_cvt_pk_bf16_f32 v56, v52, v53
	v_mul_f32_e32 v53, v53, v53
	v_fmac_f32_e32 v53, v52, v52
	v_fmac_f32_e32 v53, v54, v54
	v_fmac_f32_e32 v53, v55, v55
	v_fmac_f32_e32 v53, v48, v48
	v_fmac_f32_e32 v53, v49, v49
	v_fmac_f32_e32 v53, v50, v50
	v_fmac_f32_e32 v53, v51, v51
	v_add_f32_e32 v52, v61, v53
	ds_swizzle_b32 v53, v52 offset:swizzle(SWAP,16)
	v_cvt_pk_bf16_f32 v58, v48, v49
	v_cvt_pk_bf16_f32 v57, v54, v55
	v_cvt_pk_bf16_f32 v59, v50, v51
	global_store_dwordx4 v[74:75], v[56:59], off offset:256
	s_waitcnt lgkmcnt(0)
	v_add_f32_e32 v48, v52, v53
	v_mov_b32_e32 v49, v48
	s_nop 1
	v_permlane32_swap_b32_e32 v48, v49
	s_and_saveexec_b64 s[40:41], s[8:9]
	s_cbranch_execz .LBB0_546
	v_add_f32_e32 v50, v48, v49
	v_lshlrev_b64 v[48:49], 7, v[64:65]
	v_lshl_add_u64 v[48:49], s[18:19], 0, v[48:49]
	v_lshl_add_u64 v[48:49], s[38:39], 2, v[48:49]
	s_lshl_b32 s24, s55, 2
	v_lshl_add_u64 v[48:49], v[48:49], 0, s[24:25]
	global_store_dword v[48:49], v50, off
.LBB0_546:
	s_or_b64 exec, exec, s[40:41]
	v_add_u32_e32 v48, 0x90, v146
	v_ashrrev_i32_e32 v49, 31, v48
	v_lshlrev_b64 v[50:51], 11, v[48:49]
	v_lshl_add_u64 v[58:59], v[50:51], 0, v[144:145]
	v_lshlrev_b64 v[60:61], 2, v[58:59]
	v_lshl_add_u64 v[62:63], s[16:17], 0, v[60:61]
	v_lshl_add_u64 v[58:59], v[58:59], 1, s[14:15]
	v_lshl_add_u64 v[60:61], s[22:23], 0, v[60:61]
	s_waitcnt vmcnt(9)
	v_pk_add_f32 v[46:47], v[46:47], v[224:225]
	v_pk_add_f32 v[44:45], v[44:45], v[222:223]
	s_waitcnt vmcnt(8)
	v_pk_add_f32 v[42:43], v[42:43], v[228:229]
	v_pk_add_f32 v[40:41], v[40:41], v[226:227]
	v_cvt_pk_bf16_f32 v50, v44, v45
	v_cvt_pk_bf16_f32 v51, v46, v47
	v_cvt_pk_bf16_f32 v52, v40, v41
	v_cvt_pk_bf16_f32 v53, v42, v43
	global_store_dwordx4 v[60:61], v[44:47], off
	global_store_dwordx4 v[60:61], v[40:43], off offset:16
	global_store_dwordx4 v[58:59], v[50:53], off
	v_mul_f32_e32 v45, v45, v45
	v_fmac_f32_e32 v45, v44, v44
	v_fmac_f32_e32 v45, v46, v46
	v_fmac_f32_e32 v45, v47, v47
	v_fmac_f32_e32 v45, v40, v40
	v_fmac_f32_e32 v45, v41, v41
	v_fmac_f32_e32 v45, v42, v42
	v_fmac_f32_e32 v45, v43, v43
	s_waitcnt vmcnt(10)
	v_pk_add_f32 v[38:39], v[38:39], v[240:241]
	v_pk_add_f32 v[36:37], v[36:37], v[238:239]
	s_waitcnt vmcnt(9)
	v_pk_add_f32 v[34:35], v[34:35], v[244:245]
	v_pk_add_f32 v[32:33], v[32:33], v[242:243]
	global_store_dwordx4 v[60:61], v[36:39], off offset:512
	global_store_dwordx4 v[60:61], v[32:35], off offset:528
	v_cvt_pk_bf16_f32 v40, v36, v37
	v_mul_f32_e32 v37, v37, v37
	v_fmac_f32_e32 v37, v36, v36
	v_fmac_f32_e32 v37, v38, v38
	v_fmac_f32_e32 v37, v39, v39
	v_fmac_f32_e32 v37, v32, v32
	v_fmac_f32_e32 v37, v33, v33
	v_fmac_f32_e32 v37, v34, v34
	v_fmac_f32_e32 v37, v35, v35
	v_add_f32_e32 v36, v45, v37
	ds_swizzle_b32 v37, v36 offset:swizzle(SWAP,16)
	v_cvt_pk_bf16_f32 v42, v32, v33
	v_cvt_pk_bf16_f32 v41, v38, v39
	v_cvt_pk_bf16_f32 v43, v34, v35
	global_store_dwordx4 v[58:59], v[40:43], off offset:256
	s_waitcnt lgkmcnt(0)
	v_add_f32_e32 v32, v36, v37
	v_mov_b32_e32 v33, v32
	s_nop 1
	v_permlane32_swap_b32_e32 v32, v33
	s_and_saveexec_b64 s[40:41], s[8:9]
	s_cbranch_execz .LBB0_548
	v_add_f32_e32 v34, v32, v33
	v_lshlrev_b64 v[32:33], 7, v[48:49]
	v_lshl_add_u64 v[32:33], s[18:19], 0, v[32:33]
	v_lshl_add_u64 v[32:33], s[38:39], 2, v[32:33]
	s_lshl_b32 s24, s55, 2
	v_lshl_add_u64 v[32:33], v[32:33], 0, s[24:25]
	global_store_dword v[32:33], v34, off
; __device__ __forceinline__ float swz16(float v) { return __builtin_bit_cast(float, __builtin_amdgcn_ds_swizzle(__builtin_bit_cast(int, v), 0x401F)); }
;     __device__ __forceinline__ void operator()(const f32x4 (&acc)[2][2][4][2], const Unit& u, int wr, int wc, int fr, int fq) const {
;     ...
;         for (int ai = 0; ai < 2; ++ai)
; #pragma unroll
;             for (int m = 0; m < 4; ++m) {
;                 const int row = row0 + ai * 128 + m * 16; float sq = 0.f;
; #pragma unroll
;                 for (int bj = 0; bj < 2; ++bj) {
;                     const size_t off = (size_t)row * DM + col0 + bj * 128;
;                     const f32x4 r0 = *(const f32x4*)(res + off), r1 = *(const f32x4*)(res + off + 4);
;                     const f32x4 v0 = acc[ai][bj][m][0] + r0, v1 = acc[ai][bj][m][1] + r1;
;                     *(f32x4*)(out + off) = v0; *(f32x4*)(out + off + 4) = v1;
;                     u32x4 o; o.x = pack2(v0[0], v0[1]); o.y = pack2(v0[2], v0[3]); o.z = pack2(v1[0], v1[1]); o.w = pack2(v1[2], v1[3]);
;                     *(u32x4*)(hb + off) = o;
;                     sq += v0[0] * v0[0] + v0[1] * v0[1] + v0[2] * v0[2] + v0[3] * v0[3] + v1[0] * v1[0] + v1[1] * v1[1] + v1[2] * v1[2] + v1[3] * v1[3];
;                 }
;                 sq += swz16(sq); sq = sum32(sq);
;                 if (fq == 0) ss_out[(size_t)row * 32 + u.pn * 4 + wc] = sq;
;             }
.LBB0_548:
	s_or_b64 exec, exec, s[40:41]
	v_add_u32_e32 v32, 0xa0, v146
	v_ashrrev_i32_e32 v33, 31, v32
	v_lshlrev_b64 v[34:35], 11, v[32:33]
	v_lshl_add_u64 v[42:43], v[34:35], 0, v[144:145]
	v_lshlrev_b64 v[44:45], 2, v[42:43]
	v_lshl_add_u64 v[46:47], s[16:17], 0, v[44:45]
	global_load_dwordx4 v[34:37], v[46:47], off
	global_load_dwordx4 v[38:41], v[46:47], off offset:16
	global_load_dwordx4 v[230:233], v[46:47], off offset:512
	global_load_dwordx4 v[234:237], v[46:47], off offset:528
	s_mov_b32 s100, 0x20000
	s_mov_b32 s101, 0
	v_lshl_add_u64 v[242:243], v[46:47], 0, s[100:101]
	global_load_dwordx4 v[222:225], v[242:243], off
	global_load_dwordx4 v[226:229], v[242:243], off offset:16
	global_load_dwordx4 v[238:241], v[242:243], off offset:512
	global_load_dwordx4 v[242:245], v[242:243], off offset:528
	v_lshl_add_u64 v[42:43], v[42:43], 1, s[14:15]
	v_lshl_add_u64 v[44:45], s[22:23], 0, v[44:45]
	s_waitcnt vmcnt(7)
	v_pk_add_f32 v[30:31], v[30:31], v[36:37]
	v_pk_add_f32 v[28:29], v[28:29], v[34:35]
	s_waitcnt vmcnt(6)
	v_pk_add_f32 v[26:27], v[26:27], v[40:41]
	v_pk_add_f32 v[24:25], v[24:25], v[38:39]
	v_cvt_pk_bf16_f32 v34, v28, v29
	v_cvt_pk_bf16_f32 v35, v30, v31
	v_cvt_pk_bf16_f32 v36, v24, v25
	v_cvt_pk_bf16_f32 v37, v26, v27
	global_store_dwordx4 v[44:45], v[28:31], off
	global_store_dwordx4 v[44:45], v[24:27], off offset:16
	global_store_dwordx4 v[42:43], v[34:37], off
	v_mul_f32_e32 v29, v29, v29
	v_fmac_f32_e32 v29, v28, v28
	v_fmac_f32_e32 v29, v30, v30
	v_fmac_f32_e32 v29, v31, v31
	v_fmac_f32_e32 v29, v24, v24
	v_fmac_f32_e32 v29, v25, v25
	v_fmac_f32_e32 v29, v26, v26
	v_fmac_f32_e32 v29, v27, v27
	s_waitcnt vmcnt(8)
	v_pk_add_f32 v[22:23], v[22:23], v[232:233]
	v_pk_add_f32 v[20:21], v[20:21], v[230:231]
	s_waitcnt vmcnt(7)
	v_pk_add_f32 v[18:19], v[18:19], v[236:237]
	v_pk_add_f32 v[16:17], v[16:17], v[234:235]
	global_store_dwordx4 v[44:45], v[20:23], off offset:512
	global_store_dwordx4 v[44:45], v[16:19], off offset:528
	v_cvt_pk_bf16_f32 v24, v20, v21
	v_mul_f32_e32 v21, v21, v21
	v_fmac_f32_e32 v21, v20, v20
	v_fmac_f32_e32 v21, v22, v22
	v_fmac_f32_e32 v21, v23, v23
	v_fmac_f32_e32 v21, v16, v16
	v_fmac_f32_e32 v21, v17, v17
	v_fmac_f32_e32 v21, v18, v18
	v_fmac_f32_e32 v21, v19, v19
	v_add_f32_e32 v20, v29, v21
	ds_swizzle_b32 v21, v20 offset:swizzle(SWAP,16)
	v_cvt_pk_bf16_f32 v26, v16, v17
	v_cvt_pk_bf16_f32 v25, v22, v23
	v_cvt_pk_bf16_f32 v27, v18, v19
	global_store_dwordx4 v[42:43], v[24:27], off offset:256
	s_waitcnt lgkmcnt(0)
	v_add_f32_e32 v16, v20, v21
	v_mov_b32_e32 v17, v16
	s_nop 1
	v_permlane32_swap_b32_e32 v16, v17
	s_and_saveexec_b64 s[40:41], s[8:9]
	s_cbranch_execz .LBB0_550
	v_add_f32_e32 v18, v16, v17
	v_lshlrev_b64 v[16:17], 7, v[32:33]
	v_lshl_add_u64 v[16:17], s[18:19], 0, v[16:17]
	v_lshl_add_u64 v[16:17], s[38:39], 2, v[16:17]
	s_lshl_b32 s24, s55, 2
	v_lshl_add_u64 v[16:17], v[16:17], 0, s[24:25]
	global_store_dword v[16:17], v18, off
.LBB0_550:
	s_or_b64 exec, exec, s[40:41]
	v_add_u32_e32 v16, 0xb0, v146
	v_ashrrev_i32_e32 v17, 31, v16
	v_lshlrev_b64 v[18:19], 11, v[16:17]
	v_lshl_add_u64 v[26:27], v[18:19], 0, v[144:145]
	v_lshlrev_b64 v[28:29], 2, v[26:27]
	v_lshl_add_u64 v[30:31], s[16:17], 0, v[28:29]
	v_lshl_add_u64 v[26:27], v[26:27], 1, s[14:15]
	v_lshl_add_u64 v[28:29], s[22:23], 0, v[28:29]
	s_waitcnt vmcnt(9)
	v_pk_add_f32 v[14:15], v[14:15], v[224:225]
	v_pk_add_f32 v[12:13], v[12:13], v[222:223]
	s_waitcnt vmcnt(8)
	v_pk_add_f32 v[10:11], v[10:11], v[228:229]
	v_pk_add_f32 v[8:9], v[8:9], v[226:227]
	v_cvt_pk_bf16_f32 v18, v12, v13
	v_cvt_pk_bf16_f32 v19, v14, v15
	v_cvt_pk_bf16_f32 v20, v8, v9
	v_cvt_pk_bf16_f32 v21, v10, v11
	global_store_dwordx4 v[28:29], v[12:15], off
	global_store_dwordx4 v[28:29], v[8:11], off offset:16
	global_store_dwordx4 v[26:27], v[18:21], off
	v_mul_f32_e32 v13, v13, v13
	v_fmac_f32_e32 v13, v12, v12
	v_fmac_f32_e32 v13, v14, v14
	v_fmac_f32_e32 v13, v15, v15
	v_fmac_f32_e32 v13, v8, v8
	v_fmac_f32_e32 v13, v9, v9
	v_fmac_f32_e32 v13, v10, v10
	v_fmac_f32_e32 v13, v11, v11
	s_waitcnt vmcnt(10)
	v_pk_add_f32 v[6:7], v[6:7], v[240:241]
	v_pk_add_f32 v[4:5], v[4:5], v[238:239]
	s_waitcnt vmcnt(9)
	v_pk_add_f32 v[2:3], v[2:3], v[244:245]
	v_pk_add_f32 v[0:1], v[0:1], v[242:243]
	global_store_dwordx4 v[28:29], v[4:7], off offset:512
	global_store_dwordx4 v[28:29], v[0:3], off offset:528
	v_cvt_pk_bf16_f32 v8, v4, v5
	v_mul_f32_e32 v5, v5, v5
	v_fmac_f32_e32 v5, v4, v4
	v_fmac_f32_e32 v5, v6, v6
	v_fmac_f32_e32 v5, v7, v7
	v_fmac_f32_e32 v5, v0, v0
	v_fmac_f32_e32 v5, v1, v1
	v_fmac_f32_e32 v5, v2, v2
	v_fmac_f32_e32 v5, v3, v3
	v_add_f32_e32 v4, v13, v5
	ds_swizzle_b32 v5, v4 offset:swizzle(SWAP,16)
	v_cvt_pk_bf16_f32 v10, v0, v1
	v_cvt_pk_bf16_f32 v9, v6, v7
	v_cvt_pk_bf16_f32 v11, v2, v3
	global_store_dwordx4 v[26:27], v[8:11], off offset:256
	s_waitcnt lgkmcnt(0)
	v_add_f32_e32 v0, v4, v5
	v_mov_b32_e32 v1, v0
	s_nop 1
	v_permlane32_swap_b32_e32 v0, v1
	s_and_saveexec_b64 s[40:41], s[8:9]
	s_cbranch_execz .LBB0_527
	v_add_f32_e32 v2, v0, v1
	v_lshlrev_b64 v[0:1], 7, v[16:17]
	v_lshl_add_u64 v[0:1], s[18:19], 0, v[0:1]
	v_lshl_add_u64 v[0:1], s[38:39], 2, v[0:1]
	s_lshl_b32 s24, s55, 2
	v_lshl_add_u64 v[0:1], v[0:1], 0, s[24:25]
	global_store_dword v[0:1], v2, off
	s_branch .LBB0_527

; __device__ __forceinline__ float swz16(float v) { return __builtin_bit_cast(float, __builtin_amdgcn_ds_swizzle(__builtin_bit_cast(int, v), 0x401F)); }
;     __device__ __forceinline__ void operator()(const f32x4 (&acc)[2][2][4][2], const Unit& u, int wr, int wc, int fr, int fq) const {
;     ...
;         for (int ai = 0; ai < 2; ++ai)
; #pragma unroll
;             for (int m = 0; m < 4; ++m) {
;                 const int row = row0 + ai * 128 + m * 16; float sq = 0.f;
; #pragma unroll
;                 for (int bj = 0; bj < 2; ++bj) {
;                     const size_t off = (size_t)row * DM + col0 + bj * 128;
;                     const f32x4 r0 = *(const f32x4*)(res + off), r1 = *(const f32x4*)(res + off + 4);
;                     const f32x4 v0 = acc[ai][bj][m][0] + r0, v1 = acc[ai][bj][m][1] + r1;
;                     *(f32x4*)(out + off) = v0; *(f32x4*)(out + off + 4) = v1;
;                     u32x4 o; o.x = pack2(v0[0], v0[1]); o.y = pack2(v0[2], v0[3]); o.z = pack2(v1[0], v1[1]); o.w = pack2(v1[2], v1[3]);
;                     *(u32x4*)(hb + off) = o;
;                     sq += v0[0] * v0[0] + v0[1] * v0[1] + v0[2] * v0[2] + v0[3] * v0[3] + v1[0] * v1[0] + v1[1] * v1[1] + v1[2] * v1[2] + v1[3] * v1[3];
;                 }
;                 sq += swz16(sq); sq = sum32(sq);
;                 if (fq == 0) ss_out[(size_t)row * 32 + u.pn * 4 + wc] = sq;
;             }
.LBB0_610:
	s_or_b64 exec, exec, s[38:39]
	v_or_b32_e32 v96, 32, v146
	v_ashrrev_i32_e32 v97, 31, v96
	v_lshlrev_b64 v[98:99], 11, v[96:97]
	v_lshl_add_u64 v[106:107], v[98:99], 0, v[144:145]
	v_lshl_add_u64 v[108:109], v[106:107], 2, s[12:13]
	global_load_dwordx4 v[98:101], v[108:109], off
	global_load_dwordx4 v[102:105], v[108:109], off offset:16
	global_load_dwordx4 v[230:233], v[108:109], off offset:512
	global_load_dwordx4 v[234:237], v[108:109], off offset:528
	s_mov_b32 s100, 0x20000
	s_mov_b32 s101, 0
	v_lshl_add_u64 v[242:243], v[108:109], 0, s[100:101]
	global_load_dwordx4 v[222:225], v[242:243], off
	global_load_dwordx4 v[226:229], v[242:243], off offset:16
	global_load_dwordx4 v[238:241], v[242:243], off offset:512
	global_load_dwordx4 v[242:245], v[242:243], off offset:528
	v_lshl_add_u64 v[106:107], v[106:107], 1, s[16:17]
	s_waitcnt vmcnt(7)
	v_pk_add_f32 v[94:95], v[94:95], v[100:101]
	v_pk_add_f32 v[92:93], v[92:93], v[98:99]
	s_waitcnt vmcnt(6)
	v_pk_add_f32 v[90:91], v[90:91], v[104:105]
	v_pk_add_f32 v[88:89], v[88:89], v[102:103]
	v_cvt_pk_bf16_f32 v98, v92, v93
	v_cvt_pk_bf16_f32 v99, v94, v95
	v_cvt_pk_bf16_f32 v100, v88, v89
	v_cvt_pk_bf16_f32 v101, v90, v91
	global_store_dwordx4 v[108:109], v[92:95], off
	global_store_dwordx4 v[108:109], v[88:91], off offset:16
	global_store_dwordx4 v[106:107], v[98:101], off
	v_mul_f32_e32 v93, v93, v93
	v_fmac_f32_e32 v93, v92, v92
	v_fmac_f32_e32 v93, v94, v94
	v_fmac_f32_e32 v93, v95, v95
	v_fmac_f32_e32 v93, v88, v88
	v_fmac_f32_e32 v93, v89, v89
	v_fmac_f32_e32 v93, v90, v90
	v_fmac_f32_e32 v93, v91, v91
	s_waitcnt vmcnt(8)
	v_pk_add_f32 v[86:87], v[86:87], v[232:233]
	v_pk_add_f32 v[84:85], v[84:85], v[230:231]
	s_waitcnt vmcnt(7)
	v_pk_add_f32 v[82:83], v[82:83], v[236:237]
	v_pk_add_f32 v[80:81], v[80:81], v[234:235]
	global_store_dwordx4 v[108:109], v[84:87], off offset:512
	global_store_dwordx4 v[108:109], v[80:83], off offset:528
	v_cvt_pk_bf16_f32 v88, v84, v85
	v_mul_f32_e32 v85, v85, v85
	v_fmac_f32_e32 v85, v84, v84
	v_fmac_f32_e32 v85, v86, v86
	v_fmac_f32_e32 v85, v87, v87
	v_fmac_f32_e32 v85, v80, v80
	v_fmac_f32_e32 v85, v81, v81
	v_fmac_f32_e32 v85, v82, v82
	v_fmac_f32_e32 v85, v83, v83
	v_add_f32_e32 v84, v93, v85
	ds_swizzle_b32 v85, v84 offset:swizzle(SWAP,16)
	v_cvt_pk_bf16_f32 v90, v80, v81
	v_cvt_pk_bf16_f32 v89, v86, v87
	v_cvt_pk_bf16_f32 v91, v82, v83
	global_store_dwordx4 v[106:107], v[88:91], off offset:256
	s_waitcnt lgkmcnt(0)
	v_add_f32_e32 v80, v84, v85
	v_mov_b32_e32 v81, v80
	s_nop 1
	v_permlane32_swap_b32_e32 v80, v81
	s_and_saveexec_b64 s[38:39], s[8:9]
	s_cbranch_execz .LBB0_612
	v_add_f32_e32 v82, v80, v81
	v_lshlrev_b64 v[80:81], 7, v[96:97]
	v_lshl_add_u64 v[80:81], s[20:21], 0, v[80:81]
	v_lshl_add_u64 v[80:81], s[36:37], 2, v[80:81]
	s_lshl_b32 s22, s53, 2
	v_lshl_add_u64 v[80:81], v[80:81], 0, s[22:23]
	global_store_dword v[80:81], v82, off
.LBB0_612:
	s_or_b64 exec, exec, s[38:39]
	v_or_b32_e32 v80, 48, v146
	v_ashrrev_i32_e32 v81, 31, v80
	v_lshlrev_b64 v[82:83], 11, v[80:81]
	v_lshl_add_u64 v[90:91], v[82:83], 0, v[144:145]
	v_lshl_add_u64 v[92:93], v[90:91], 2, s[12:13]
	v_lshl_add_u64 v[90:91], v[90:91], 1, s[16:17]
	s_waitcnt vmcnt(9)
	v_pk_add_f32 v[78:79], v[78:79], v[224:225]
	v_pk_add_f32 v[76:77], v[76:77], v[222:223]
	s_waitcnt vmcnt(8)
	v_pk_add_f32 v[74:75], v[74:75], v[228:229]
	v_pk_add_f32 v[72:73], v[72:73], v[226:227]
	v_cvt_pk_bf16_f32 v82, v76, v77
	v_cvt_pk_bf16_f32 v83, v78, v79
	v_cvt_pk_bf16_f32 v84, v72, v73
	v_cvt_pk_bf16_f32 v85, v74, v75
	global_store_dwordx4 v[92:93], v[76:79], off
	global_store_dwordx4 v[92:93], v[72:75], off offset:16
	global_store_dwordx4 v[90:91], v[82:85], off
	v_mul_f32_e32 v77, v77, v77
	v_fmac_f32_e32 v77, v76, v76
	v_fmac_f32_e32 v77, v78, v78
	v_fmac_f32_e32 v77, v79, v79
	v_fmac_f32_e32 v77, v72, v72
	v_fmac_f32_e32 v77, v73, v73
	v_fmac_f32_e32 v77, v74, v74
	v_fmac_f32_e32 v77, v75, v75
	s_waitcnt vmcnt(10)
	v_pk_add_f32 v[70:71], v[70:71], v[240:241]
	v_pk_add_f32 v[68:69], v[68:69], v[238:239]
	s_waitcnt vmcnt(9)
	v_pk_add_f32 v[66:67], v[66:67], v[244:245]
	v_pk_add_f32 v[64:65], v[64:65], v[242:243]
	global_store_dwordx4 v[92:93], v[68:71], off offset:512
	global_store_dwordx4 v[92:93], v[64:67], off offset:528
	v_cvt_pk_bf16_f32 v72, v68, v69
	v_mul_f32_e32 v69, v69, v69
	v_fmac_f32_e32 v69, v68, v68
	v_fmac_f32_e32 v69, v70, v70
	v_fmac_f32_e32 v69, v71, v71
	v_fmac_f32_e32 v69, v64, v64
	v_fmac_f32_e32 v69, v65, v65
	v_fmac_f32_e32 v69, v66, v66
	v_fmac_f32_e32 v69, v67, v67
	v_add_f32_e32 v68, v77, v69
	ds_swizzle_b32 v69, v68 offset:swizzle(SWAP,16)
	v_cvt_pk_bf16_f32 v74, v64, v65
	v_cvt_pk_bf16_f32 v73, v70, v71
	v_cvt_pk_bf16_f32 v75, v66, v67
	global_store_dwordx4 v[90:91], v[72:75], off offset:256
	s_waitcnt lgkmcnt(0)
	v_add_f32_e32 v64, v68, v69
	v_mov_b32_e32 v65, v64
	s_nop 1
	v_permlane32_swap_b32_e32 v64, v65
	s_and_saveexec_b64 s[38:39], s[8:9]
	s_cbranch_execz .LBB0_614
	v_add_f32_e32 v66, v64, v65
	v_lshlrev_b64 v[64:65], 7, v[80:81]
	v_lshl_add_u64 v[64:65], s[20:21], 0, v[64:65]
	v_lshl_add_u64 v[64:65], s[36:37], 2, v[64:65]
	s_lshl_b32 s22, s53, 2
	v_lshl_add_u64 v[64:65], v[64:65], 0, s[22:23]
	global_store_dword v[64:65], v66, off
; __device__ __forceinline__ float swz16(float v) { return __builtin_bit_cast(float, __builtin_amdgcn_ds_swizzle(__builtin_bit_cast(int, v), 0x401F)); }
;     __device__ __forceinline__ void operator()(const f32x4 (&acc)[2][2][4][2], const Unit& u, int wr, int wc, int fr, int fq) const {
;     ...
;         for (int ai = 0; ai < 2; ++ai)
; #pragma unroll
;             for (int m = 0; m < 4; ++m) {
;                 const int row = row0 + ai * 128 + m * 16; float sq = 0.f;
; #pragma unroll
;                 for (int bj = 0; bj < 2; ++bj) {
;                     const size_t off = (size_t)row * DM + col0 + bj * 128;
;                     const f32x4 r0 = *(const f32x4*)(res + off), r1 = *(const f32x4*)(res + off + 4);
;                     const f32x4 v0 = acc[ai][bj][m][0] + r0, v1 = acc[ai][bj][m][1] + r1;
;                     *(f32x4*)(out + off) = v0; *(f32x4*)(out + off + 4) = v1;
;                     u32x4 o; o.x = pack2(v0[0], v0[1]); o.y = pack2(v0[2], v0[3]); o.z = pack2(v1[0], v1[1]); o.w = pack2(v1[2], v1[3]);
;                     *(u32x4*)(hb + off) = o;
;                     sq += v0[0] * v0[0] + v0[1] * v0[1] + v0[2] * v0[2] + v0[3] * v0[3] + v1[0] * v1[0] + v1[1] * v1[1] + v1[2] * v1[2] + v1[3] * v1[3];
;                 }
;                 sq += swz16(sq); sq = sum32(sq);
;                 if (fq == 0) ss_out[(size_t)row * 32 + u.pn * 4 + wc] = sq;
;             }
.LBB0_614:
	s_or_b64 exec, exec, s[38:39]
	v_add_u32_e32 v64, 0x80, v146
	v_ashrrev_i32_e32 v65, 31, v64
	v_lshlrev_b64 v[66:67], 11, v[64:65]
	v_lshl_add_u64 v[74:75], v[66:67], 0, v[144:145]
	v_lshl_add_u64 v[76:77], v[74:75], 2, s[12:13]
	global_load_dwordx4 v[66:69], v[76:77], off
	global_load_dwordx4 v[70:73], v[76:77], off offset:16
	global_load_dwordx4 v[230:233], v[76:77], off offset:512
	global_load_dwordx4 v[234:237], v[76:77], off offset:528
	s_mov_b32 s100, 0x20000
	s_mov_b32 s101, 0
	v_lshl_add_u64 v[242:243], v[76:77], 0, s[100:101]
	global_load_dwordx4 v[222:225], v[242:243], off
	global_load_dwordx4 v[226:229], v[242:243], off offset:16
	global_load_dwordx4 v[238:241], v[242:243], off offset:512
	global_load_dwordx4 v[242:245], v[242:243], off offset:528
	v_lshl_add_u64 v[74:75], v[74:75], 1, s[16:17]
	s_waitcnt vmcnt(7)
	v_pk_add_f32 v[62:63], v[62:63], v[68:69]
	v_pk_add_f32 v[60:61], v[60:61], v[66:67]
	s_waitcnt vmcnt(6)
	v_pk_add_f32 v[58:59], v[58:59], v[72:73]
	v_pk_add_f32 v[56:57], v[56:57], v[70:71]
	v_cvt_pk_bf16_f32 v66, v60, v61
	v_cvt_pk_bf16_f32 v67, v62, v63
	v_cvt_pk_bf16_f32 v68, v56, v57
	v_cvt_pk_bf16_f32 v69, v58, v59
	global_store_dwordx4 v[76:77], v[60:63], off
	global_store_dwordx4 v[76:77], v[56:59], off offset:16
	global_store_dwordx4 v[74:75], v[66:69], off
	v_mul_f32_e32 v61, v61, v61
	v_fmac_f32_e32 v61, v60, v60
	v_fmac_f32_e32 v61, v62, v62
	v_fmac_f32_e32 v61, v63, v63
	v_fmac_f32_e32 v61, v56, v56
	v_fmac_f32_e32 v61, v57, v57
	v_fmac_f32_e32 v61, v58, v58
	v_fmac_f32_e32 v61, v59, v59
	s_waitcnt vmcnt(8)
	v_pk_add_f32 v[54:55], v[54:55], v[232:233]
	v_pk_add_f32 v[52:53], v[52:53], v[230:231]
	s_waitcnt vmcnt(7)
	v_pk_add_f32 v[50:51], v[50:51], v[236:237]
	v_pk_add_f32 v[48:49], v[48:49], v[234:235]
	global_store_dwordx4 v[76:77], v[52:55], off offset:512
	global_store_dwordx4 v[76:77], v[48:51], off offset:528
	v_cvt_pk_bf16_f32 v56, v52, v53
	v_mul_f32_e32 v53, v53, v53
	v_fmac_f32_e32 v53, v52, v52
	v_fmac_f32_e32 v53, v54, v54
	v_fmac_f32_e32 v53, v55, v55
	v_fmac_f32_e32 v53, v48, v48
	v_fmac_f32_e32 v53, v49, v49
	v_fmac_f32_e32 v53, v50, v50
	v_fmac_f32_e32 v53, v51, v51
	v_add_f32_e32 v52, v61, v53
	ds_swizzle_b32 v53, v52 offset:swizzle(SWAP,16)
	v_cvt_pk_bf16_f32 v58, v48, v49
	v_cvt_pk_bf16_f32 v57, v54, v55
	v_cvt_pk_bf16_f32 v59, v50, v51
	global_store_dwordx4 v[74:75], v[56:59], off offset:256
	s_waitcnt lgkmcnt(0)
	v_add_f32_e32 v48, v52, v53
	v_mov_b32_e32 v49, v48
	s_nop 1
	v_permlane32_swap_b32_e32 v48, v49
	s_and_saveexec_b64 s[38:39], s[8:9]
	s_cbranch_execz .LBB0_616
	v_add_f32_e32 v50, v48, v49
	v_lshlrev_b64 v[48:49], 7, v[64:65]
	v_lshl_add_u64 v[48:49], s[20:21], 0, v[48:49]
	v_lshl_add_u64 v[48:49], s[36:37], 2, v[48:49]
	s_lshl_b32 s22, s53, 2
	v_lshl_add_u64 v[48:49], v[48:49], 0, s[22:23]
	global_store_dword v[48:49], v50, off
.LBB0_616:
	s_or_b64 exec, exec, s[38:39]
	v_add_u32_e32 v48, 0x90, v146
	v_ashrrev_i32_e32 v49, 31, v48
	v_lshlrev_b64 v[50:51], 11, v[48:49]
	v_lshl_add_u64 v[58:59], v[50:51], 0, v[144:145]
	v_lshl_add_u64 v[60:61], v[58:59], 2, s[12:13]
	v_lshl_add_u64 v[58:59], v[58:59], 1, s[16:17]
	s_waitcnt vmcnt(9)
	v_pk_add_f32 v[46:47], v[46:47], v[224:225]
	v_pk_add_f32 v[44:45], v[44:45], v[222:223]
	s_waitcnt vmcnt(8)
	v_pk_add_f32 v[42:43], v[42:43], v[228:229]
	v_pk_add_f32 v[40:41], v[40:41], v[226:227]
	v_cvt_pk_bf16_f32 v50, v44, v45
	v_cvt_pk_bf16_f32 v51, v46, v47
	v_cvt_pk_bf16_f32 v52, v40, v41
	v_cvt_pk_bf16_f32 v53, v42, v43
	global_store_dwordx4 v[60:61], v[44:47], off
	global_store_dwordx4 v[60:61], v[40:43], off offset:16
	global_store_dwordx4 v[58:59], v[50:53], off
	v_mul_f32_e32 v45, v45, v45
	v_fmac_f32_e32 v45, v44, v44
	v_fmac_f32_e32 v45, v46, v46
	v_fmac_f32_e32 v45, v47, v47
	v_fmac_f32_e32 v45, v40, v40
	v_fmac_f32_e32 v45, v41, v41
	v_fmac_f32_e32 v45, v42, v42
	v_fmac_f32_e32 v45, v43, v43
	s_waitcnt vmcnt(10)
	v_pk_add_f32 v[38:39], v[38:39], v[240:241]
	v_pk_add_f32 v[36:37], v[36:37], v[238:239]
	s_waitcnt vmcnt(9)
	v_pk_add_f32 v[34:35], v[34:35], v[244:245]
	v_pk_add_f32 v[32:33], v[32:33], v[242:243]
	global_store_dwordx4 v[60:61], v[36:39], off offset:512
	global_store_dwordx4 v[60:61], v[32:35], off offset:528
	v_cvt_pk_bf16_f32 v40, v36, v37
	v_mul_f32_e32 v37, v37, v37
	v_fmac_f32_e32 v37, v36, v36
	v_fmac_f32_e32 v37, v38, v38
	v_fmac_f32_e32 v37, v39, v39
	v_fmac_f32_e32 v37, v32, v32
	v_fmac_f32_e32 v37, v33, v33
	v_fmac_f32_e32 v37, v34, v34
	v_fmac_f32_e32 v37, v35, v35
	v_add_f32_e32 v36, v45, v37
	ds_swizzle_b32 v37, v36 offset:swizzle(SWAP,16)
	v_cvt_pk_bf16_f32 v42, v32, v33
	v_cvt_pk_bf16_f32 v41, v38, v39
	v_cvt_pk_bf16_f32 v43, v34, v35
	global_store_dwordx4 v[58:59], v[40:43], off offset:256
	s_waitcnt lgkmcnt(0)
	v_add_f32_e32 v32, v36, v37
	v_mov_b32_e32 v33, v32
	s_nop 1
	v_permlane32_swap_b32_e32 v32, v33
	s_and_saveexec_b64 s[38:39], s[8:9]
	s_cbranch_execz .LBB0_618
	v_add_f32_e32 v34, v32, v33
	v_lshlrev_b64 v[32:33], 7, v[48:49]
	v_lshl_add_u64 v[32:33], s[20:21], 0, v[32:33]
	v_lshl_add_u64 v[32:33], s[36:37], 2, v[32:33]
	s_lshl_b32 s22, s53, 2
	v_lshl_add_u64 v[32:33], v[32:33], 0, s[22:23]
	global_store_dword v[32:33], v34, off
; __device__ __forceinline__ float swz16(float v) { return __builtin_bit_cast(float, __builtin_amdgcn_ds_swizzle(__builtin_bit_cast(int, v), 0x401F)); }
;     __device__ __forceinline__ void operator()(const f32x4 (&acc)[2][2][4][2], const Unit& u, int wr, int wc, int fr, int fq) const {
;     ...
;         for (int ai = 0; ai < 2; ++ai)
; #pragma unroll
;             for (int m = 0; m < 4; ++m) {
;                 const int row = row0 + ai * 128 + m * 16; float sq = 0.f;
; #pragma unroll
;                 for (int bj = 0; bj < 2; ++bj) {
;                     const size_t off = (size_t)row * DM + col0 + bj * 128;
;                     const f32x4 r0 = *(const f32x4*)(res + off), r1 = *(const f32x4*)(res + off + 4);
;                     const f32x4 v0 = acc[ai][bj][m][0] + r0, v1 = acc[ai][bj][m][1] + r1;
;                     *(f32x4*)(out + off) = v0; *(f32x4*)(out + off + 4) = v1;
;                     u32x4 o; o.x = pack2(v0[0], v0[1]); o.y = pack2(v0[2], v0[3]); o.z = pack2(v1[0], v1[1]); o.w = pack2(v1[2], v1[3]);
;                     *(u32x4*)(hb + off) = o;
;                     sq += v0[0] * v0[0] + v0[1] * v0[1] + v0[2] * v0[2] + v0[3] * v0[3] + v1[0] * v1[0] + v1[1] * v1[1] + v1[2] * v1[2] + v1[3] * v1[3];
;                 }
;                 sq += swz16(sq); sq = sum32(sq);
;                 if (fq == 0) ss_out[(size_t)row * 32 + u.pn * 4 + wc] = sq;
;             }
.LBB0_618:
	s_or_b64 exec, exec, s[38:39]
	v_add_u32_e32 v32, 0xa0, v146
	v_ashrrev_i32_e32 v33, 31, v32
	v_lshlrev_b64 v[34:35], 11, v[32:33]
	v_lshl_add_u64 v[42:43], v[34:35], 0, v[144:145]
	v_lshl_add_u64 v[44:45], v[42:43], 2, s[12:13]
	global_load_dwordx4 v[34:37], v[44:45], off
	global_load_dwordx4 v[38:41], v[44:45], off offset:16
	global_load_dwordx4 v[230:233], v[44:45], off offset:512
	global_load_dwordx4 v[234:237], v[44:45], off offset:528
	s_mov_b32 s100, 0x20000
	s_mov_b32 s101, 0
	v_lshl_add_u64 v[242:243], v[44:45], 0, s[100:101]
	global_load_dwordx4 v[222:225], v[242:243], off
	global_load_dwordx4 v[226:229], v[242:243], off offset:16
	global_load_dwordx4 v[238:241], v[242:243], off offset:512
	global_load_dwordx4 v[242:245], v[242:243], off offset:528
	v_lshl_add_u64 v[42:43], v[42:43], 1, s[16:17]
	s_waitcnt vmcnt(7)
	v_pk_add_f32 v[30:31], v[30:31], v[36:37]
	v_pk_add_f32 v[28:29], v[28:29], v[34:35]
	s_waitcnt vmcnt(6)
	v_pk_add_f32 v[26:27], v[26:27], v[40:41]
	v_pk_add_f32 v[24:25], v[24:25], v[38:39]
	v_cvt_pk_bf16_f32 v34, v28, v29
	v_cvt_pk_bf16_f32 v35, v30, v31
	v_cvt_pk_bf16_f32 v36, v24, v25
	v_cvt_pk_bf16_f32 v37, v26, v27
	global_store_dwordx4 v[44:45], v[28:31], off
	global_store_dwordx4 v[44:45], v[24:27], off offset:16
	global_store_dwordx4 v[42:43], v[34:37], off
	v_mul_f32_e32 v29, v29, v29
	v_fmac_f32_e32 v29, v28, v28
	v_fmac_f32_e32 v29, v30, v30
	v_fmac_f32_e32 v29, v31, v31
	v_fmac_f32_e32 v29, v24, v24
	v_fmac_f32_e32 v29, v25, v25
	v_fmac_f32_e32 v29, v26, v26
	v_fmac_f32_e32 v29, v27, v27
	s_waitcnt vmcnt(8)
	v_pk_add_f32 v[22:23], v[22:23], v[232:233]
	v_pk_add_f32 v[20:21], v[20:21], v[230:231]
	s_waitcnt vmcnt(7)
	v_pk_add_f32 v[18:19], v[18:19], v[236:237]
	v_pk_add_f32 v[16:17], v[16:17], v[234:235]
	global_store_dwordx4 v[44:45], v[20:23], off offset:512
	global_store_dwordx4 v[44:45], v[16:19], off offset:528
	v_cvt_pk_bf16_f32 v24, v20, v21
	v_mul_f32_e32 v21, v21, v21
	v_fmac_f32_e32 v21, v20, v20
	v_fmac_f32_e32 v21, v22, v22
	v_fmac_f32_e32 v21, v23, v23
	v_fmac_f32_e32 v21, v16, v16
	v_fmac_f32_e32 v21, v17, v17
	v_fmac_f32_e32 v21, v18, v18
	v_fmac_f32_e32 v21, v19, v19
	v_add_f32_e32 v20, v29, v21
	ds_swizzle_b32 v21, v20 offset:swizzle(SWAP,16)
	v_cvt_pk_bf16_f32 v26, v16, v17
	v_cvt_pk_bf16_f32 v25, v22, v23
	v_cvt_pk_bf16_f32 v27, v18, v19
	global_store_dwordx4 v[42:43], v[24:27], off offset:256
	s_waitcnt lgkmcnt(0)
	v_add_f32_e32 v16, v20, v21
	v_mov_b32_e32 v17, v16
	s_nop 1
	v_permlane32_swap_b32_e32 v16, v17
	s_and_saveexec_b64 s[38:39], s[8:9]
	s_cbranch_execz .LBB0_620
	v_add_f32_e32 v18, v16, v17
	v_lshlrev_b64 v[16:17], 7, v[32:33]
	v_lshl_add_u64 v[16:17], s[20:21], 0, v[16:17]
	v_lshl_add_u64 v[16:17], s[36:37], 2, v[16:17]
	s_lshl_b32 s22, s53, 2
	v_lshl_add_u64 v[16:17], v[16:17], 0, s[22:23]
	global_store_dword v[16:17], v18, off
.LBB0_620:
	s_or_b64 exec, exec, s[38:39]
	v_add_u32_e32 v16, 0xb0, v146
	v_ashrrev_i32_e32 v17, 31, v16
	v_lshlrev_b64 v[18:19], 11, v[16:17]
	v_lshl_add_u64 v[26:27], v[18:19], 0, v[144:145]
	v_lshl_add_u64 v[28:29], v[26:27], 2, s[12:13]
	v_lshl_add_u64 v[26:27], v[26:27], 1, s[16:17]
	s_waitcnt vmcnt(9)
	v_pk_add_f32 v[14:15], v[14:15], v[224:225]
	v_pk_add_f32 v[12:13], v[12:13], v[222:223]
	s_waitcnt vmcnt(8)
	v_pk_add_f32 v[10:11], v[10:11], v[228:229]
	v_pk_add_f32 v[8:9], v[8:9], v[226:227]
	v_cvt_pk_bf16_f32 v18, v12, v13
	v_cvt_pk_bf16_f32 v19, v14, v15
	v_cvt_pk_bf16_f32 v20, v8, v9
	v_cvt_pk_bf16_f32 v21, v10, v11
	global_store_dwordx4 v[28:29], v[12:15], off
	global_store_dwordx4 v[28:29], v[8:11], off offset:16
	global_store_dwordx4 v[26:27], v[18:21], off
	v_mul_f32_e32 v13, v13, v13
	v_fmac_f32_e32 v13, v12, v12
	v_fmac_f32_e32 v13, v14, v14
	v_fmac_f32_e32 v13, v15, v15
	v_fmac_f32_e32 v13, v8, v8
	v_fmac_f32_e32 v13, v9, v9
	v_fmac_f32_e32 v13, v10, v10
	v_fmac_f32_e32 v13, v11, v11
	s_waitcnt vmcnt(10)
	v_pk_add_f32 v[6:7], v[6:7], v[240:241]
	v_pk_add_f32 v[4:5], v[4:5], v[238:239]
	s_waitcnt vmcnt(9)
	v_pk_add_f32 v[2:3], v[2:3], v[244:245]
	v_pk_add_f32 v[0:1], v[0:1], v[242:243]
	global_store_dwordx4 v[28:29], v[4:7], off offset:512
	global_store_dwordx4 v[28:29], v[0:3], off offset:528
	v_cvt_pk_bf16_f32 v8, v4, v5
	v_mul_f32_e32 v5, v5, v5
	v_fmac_f32_e32 v5, v4, v4
	v_fmac_f32_e32 v5, v6, v6
	v_fmac_f32_e32 v5, v7, v7
	v_fmac_f32_e32 v5, v0, v0
	v_fmac_f32_e32 v5, v1, v1
	v_fmac_f32_e32 v5, v2, v2
	v_fmac_f32_e32 v5, v3, v3
	v_add_f32_e32 v4, v13, v5
	ds_swizzle_b32 v5, v4 offset:swizzle(SWAP,16)
	v_cvt_pk_bf16_f32 v10, v0, v1
	v_cvt_pk_bf16_f32 v9, v6, v7
	v_cvt_pk_bf16_f32 v11, v2, v3
	global_store_dwordx4 v[26:27], v[8:11], off offset:256
	s_waitcnt lgkmcnt(0)
	v_add_f32_e32 v0, v4, v5
	v_mov_b32_e32 v1, v0
	s_nop 1
	v_permlane32_swap_b32_e32 v0, v1
	s_and_saveexec_b64 s[38:39], s[8:9]
	s_cbranch_execz .LBB0_597
	v_add_f32_e32 v2, v0, v1
	v_lshlrev_b64 v[0:1], 7, v[16:17]
	v_lshl_add_u64 v[0:1], s[20:21], 0, v[0:1]
	v_lshl_add_u64 v[0:1], s[36:37], 2, v[0:1]
	s_lshl_b32 s22, s53, 2
	v_lshl_add_u64 v[0:1], v[0:1], 0, s[22:23]
	global_store_dword v[0:1], v2, off
	s_branch .LBB0_597

; __device__ __forceinline__ float swz16(float v) { return __builtin_bit_cast(float, __builtin_amdgcn_ds_swizzle(__builtin_bit_cast(int, v), 0x401F)); }
;     __device__ __forceinline__ void operator()(const f32x4 (&acc)[2][2][4][2], const Unit& u, int wr, int wc, int fr, int fq) const {
;     ...
;         for (int ai = 0; ai < 2; ++ai)
; #pragma unroll
;             for (int m = 0; m < 4; ++m) {
;                 const int row = row0 + ai * 128 + m * 16; float sq = 0.f;
; #pragma unroll
;                 for (int bj = 0; bj < 2; ++bj) {
;                     const size_t off = (size_t)row * DM + col0 + bj * 128;
;                     const f32x4 r0 = *(const f32x4*)(res + off), r1 = *(const f32x4*)(res + off + 4);
;                     const f32x4 v0 = acc[ai][bj][m][0] + r0, v1 = acc[ai][bj][m][1] + r1;
;                     *(f32x4*)(out + off) = v0; *(f32x4*)(out + off + 4) = v1;
;                     u32x4 o; o.x = pack2(v0[0], v0[1]); o.y = pack2(v0[2], v0[3]); o.z = pack2(v1[0], v1[1]); o.w = pack2(v1[2], v1[3]);
;                     *(u32x4*)(hb + off) = o;
;                     sq += v0[0] * v0[0] + v0[1] * v0[1] + v0[2] * v0[2] + v0[3] * v0[3] + v1[0] * v1[0] + v1[1] * v1[1] + v1[2] * v1[2] + v1[3] * v1[3];
;                 }
;                 sq += swz16(sq); sq = sum32(sq);
;                 if (fq == 0) ss_out[(size_t)row * 32 + u.pn * 4 + wc] = sq;
;             }
.LBB0_1215:
	s_or_b64 exec, exec, s[36:37]
	v_or_b32_e32 v96, 32, v146
	v_ashrrev_i32_e32 v97, 31, v96
	v_lshlrev_b64 v[98:99], 11, v[96:97]
	v_lshl_add_u64 v[106:107], v[98:99], 0, v[144:145]
	v_lshl_add_u64 v[108:109], v[106:107], 2, s[16:17]
	global_load_dwordx4 v[98:101], v[108:109], off
	global_load_dwordx4 v[102:105], v[108:109], off offset:16
	global_load_dwordx4 v[230:233], v[108:109], off offset:512
	global_load_dwordx4 v[234:237], v[108:109], off offset:528
	s_mov_b32 s100, 0x20000
	s_mov_b32 s101, 0
	v_lshl_add_u64 v[242:243], v[108:109], 0, s[100:101]
	global_load_dwordx4 v[222:225], v[242:243], off
	global_load_dwordx4 v[226:229], v[242:243], off offset:16
	global_load_dwordx4 v[238:241], v[242:243], off offset:512
	global_load_dwordx4 v[242:245], v[242:243], off offset:528
	v_lshl_add_u64 v[106:107], v[106:107], 1, s[14:15]
	s_waitcnt vmcnt(7)
	v_pk_add_f32 v[94:95], v[94:95], v[100:101]
	v_pk_add_f32 v[92:93], v[92:93], v[98:99]
	s_waitcnt vmcnt(6)
	v_pk_add_f32 v[90:91], v[90:91], v[104:105]
	v_pk_add_f32 v[88:89], v[88:89], v[102:103]
	v_cvt_pk_bf16_f32 v98, v92, v93
	v_cvt_pk_bf16_f32 v99, v94, v95
	v_cvt_pk_bf16_f32 v100, v88, v89
	v_cvt_pk_bf16_f32 v101, v90, v91
	global_store_dwordx4 v[108:109], v[92:95], off
	global_store_dwordx4 v[108:109], v[88:91], off offset:16
	global_store_dwordx4 v[106:107], v[98:101], off
	v_mul_f32_e32 v93, v93, v93
	v_fmac_f32_e32 v93, v92, v92
	v_fmac_f32_e32 v93, v94, v94
	v_fmac_f32_e32 v93, v95, v95
	v_fmac_f32_e32 v93, v88, v88
	v_fmac_f32_e32 v93, v89, v89
	v_fmac_f32_e32 v93, v90, v90
	v_fmac_f32_e32 v93, v91, v91
	s_waitcnt vmcnt(8)
	v_pk_add_f32 v[86:87], v[86:87], v[232:233]
	v_pk_add_f32 v[84:85], v[84:85], v[230:231]
	s_waitcnt vmcnt(7)
	v_pk_add_f32 v[82:83], v[82:83], v[236:237]
	v_pk_add_f32 v[80:81], v[80:81], v[234:235]
	global_store_dwordx4 v[108:109], v[84:87], off offset:512
	global_store_dwordx4 v[108:109], v[80:83], off offset:528
	v_cvt_pk_bf16_f32 v88, v84, v85
	v_mul_f32_e32 v85, v85, v85
	v_fmac_f32_e32 v85, v84, v84
	v_fmac_f32_e32 v85, v86, v86
	v_fmac_f32_e32 v85, v87, v87
	v_fmac_f32_e32 v85, v80, v80
	v_fmac_f32_e32 v85, v81, v81
	v_fmac_f32_e32 v85, v82, v82
	v_fmac_f32_e32 v85, v83, v83
	v_add_f32_e32 v84, v93, v85
	ds_swizzle_b32 v85, v84 offset:swizzle(SWAP,16)
	v_cvt_pk_bf16_f32 v90, v80, v81
	v_cvt_pk_bf16_f32 v89, v86, v87
	v_cvt_pk_bf16_f32 v91, v82, v83
	global_store_dwordx4 v[106:107], v[88:91], off offset:256
	s_waitcnt lgkmcnt(0)
	v_add_f32_e32 v80, v84, v85
	v_mov_b32_e32 v81, v80
	s_nop 1
	v_permlane32_swap_b32_e32 v80, v81
	s_and_saveexec_b64 s[36:37], s[6:7]
	s_cbranch_execz .LBB0_1217
	v_add_f32_e32 v82, v80, v81
	v_lshlrev_b64 v[80:81], 7, v[96:97]
	v_lshl_add_u64 v[80:81], s[10:11], 0, v[80:81]
	v_lshl_add_u64 v[80:81], s[34:35], 2, v[80:81]
	s_lshl_b32 s20, s47, 2
	v_lshl_add_u64 v[80:81], v[80:81], 0, s[20:21]
	global_store_dword v[80:81], v82, off
.LBB0_1217:
	s_or_b64 exec, exec, s[36:37]
	v_or_b32_e32 v80, 48, v146
	v_ashrrev_i32_e32 v81, 31, v80
	v_lshlrev_b64 v[82:83], 11, v[80:81]
	v_lshl_add_u64 v[90:91], v[82:83], 0, v[144:145]
	v_lshl_add_u64 v[92:93], v[90:91], 2, s[16:17]
	v_lshl_add_u64 v[90:91], v[90:91], 1, s[14:15]
	s_waitcnt vmcnt(9)
	v_pk_add_f32 v[78:79], v[78:79], v[224:225]
	v_pk_add_f32 v[76:77], v[76:77], v[222:223]
	s_waitcnt vmcnt(8)
	v_pk_add_f32 v[74:75], v[74:75], v[228:229]
	v_pk_add_f32 v[72:73], v[72:73], v[226:227]
	v_cvt_pk_bf16_f32 v82, v76, v77
	v_cvt_pk_bf16_f32 v83, v78, v79
	v_cvt_pk_bf16_f32 v84, v72, v73
	v_cvt_pk_bf16_f32 v85, v74, v75
	global_store_dwordx4 v[92:93], v[76:79], off
	global_store_dwordx4 v[92:93], v[72:75], off offset:16
	global_store_dwordx4 v[90:91], v[82:85], off
	v_mul_f32_e32 v77, v77, v77
	v_fmac_f32_e32 v77, v76, v76
	v_fmac_f32_e32 v77, v78, v78
	v_fmac_f32_e32 v77, v79, v79
	v_fmac_f32_e32 v77, v72, v72
	v_fmac_f32_e32 v77, v73, v73
	v_fmac_f32_e32 v77, v74, v74
	v_fmac_f32_e32 v77, v75, v75
	s_waitcnt vmcnt(10)
	v_pk_add_f32 v[70:71], v[70:71], v[240:241]
	v_pk_add_f32 v[68:69], v[68:69], v[238:239]
	s_waitcnt vmcnt(9)
	v_pk_add_f32 v[66:67], v[66:67], v[244:245]
	v_pk_add_f32 v[64:65], v[64:65], v[242:243]
	global_store_dwordx4 v[92:93], v[68:71], off offset:512
	global_store_dwordx4 v[92:93], v[64:67], off offset:528
	v_cvt_pk_bf16_f32 v72, v68, v69
	v_mul_f32_e32 v69, v69, v69
	v_fmac_f32_e32 v69, v68, v68
	v_fmac_f32_e32 v69, v70, v70
	v_fmac_f32_e32 v69, v71, v71
	v_fmac_f32_e32 v69, v64, v64
	v_fmac_f32_e32 v69, v65, v65
	v_fmac_f32_e32 v69, v66, v66
	v_fmac_f32_e32 v69, v67, v67
	v_add_f32_e32 v68, v77, v69
	ds_swizzle_b32 v69, v68 offset:swizzle(SWAP,16)
	v_cvt_pk_bf16_f32 v74, v64, v65
	v_cvt_pk_bf16_f32 v73, v70, v71
	v_cvt_pk_bf16_f32 v75, v66, v67
	global_store_dwordx4 v[90:91], v[72:75], off offset:256
	s_waitcnt lgkmcnt(0)
	v_add_f32_e32 v64, v68, v69
	v_mov_b32_e32 v65, v64
	s_nop 1
	v_permlane32_swap_b32_e32 v64, v65
	s_and_saveexec_b64 s[36:37], s[6:7]
	s_cbranch_execz .LBB0_1219
	v_add_f32_e32 v66, v64, v65
	v_lshlrev_b64 v[64:65], 7, v[80:81]
	v_lshl_add_u64 v[64:65], s[10:11], 0, v[64:65]
	v_lshl_add_u64 v[64:65], s[34:35], 2, v[64:65]
	s_lshl_b32 s20, s47, 2
	v_lshl_add_u64 v[64:65], v[64:65], 0, s[20:21]
	global_store_dword v[64:65], v66, off
; __device__ __forceinline__ float swz16(float v) { return __builtin_bit_cast(float, __builtin_amdgcn_ds_swizzle(__builtin_bit_cast(int, v), 0x401F)); }
;     __device__ __forceinline__ void operator()(const f32x4 (&acc)[2][2][4][2], const Unit& u, int wr, int wc, int fr, int fq) const {
;     ...
;         for (int ai = 0; ai < 2; ++ai)
; #pragma unroll
;             for (int m = 0; m < 4; ++m) {
;                 const int row = row0 + ai * 128 + m * 16; float sq = 0.f;
; #pragma unroll
;                 for (int bj = 0; bj < 2; ++bj) {
;                     const size_t off = (size_t)row * DM + col0 + bj * 128;
;                     const f32x4 r0 = *(const f32x4*)(res + off), r1 = *(const f32x4*)(res + off + 4);
;                     const f32x4 v0 = acc[ai][bj][m][0] + r0, v1 = acc[ai][bj][m][1] + r1;
;                     *(f32x4*)(out + off) = v0; *(f32x4*)(out + off + 4) = v1;
;                     u32x4 o; o.x = pack2(v0[0], v0[1]); o.y = pack2(v0[2], v0[3]); o.z = pack2(v1[0], v1[1]); o.w = pack2(v1[2], v1[3]);
;                     *(u32x4*)(hb + off) = o;
;                     sq += v0[0] * v0[0] + v0[1] * v0[1] + v0[2] * v0[2] + v0[3] * v0[3] + v1[0] * v1[0] + v1[1] * v1[1] + v1[2] * v1[2] + v1[3] * v1[3];
;                 }
;                 sq += swz16(sq); sq = sum32(sq);
;                 if (fq == 0) ss_out[(size_t)row * 32 + u.pn * 4 + wc] = sq;
;             }
.LBB0_1219:
	s_or_b64 exec, exec, s[36:37]
	v_add_u32_e32 v64, 0x80, v146
	v_ashrrev_i32_e32 v65, 31, v64
	v_lshlrev_b64 v[66:67], 11, v[64:65]
	v_lshl_add_u64 v[74:75], v[66:67], 0, v[144:145]
	v_lshl_add_u64 v[76:77], v[74:75], 2, s[16:17]
	global_load_dwordx4 v[66:69], v[76:77], off
	global_load_dwordx4 v[70:73], v[76:77], off offset:16
	global_load_dwordx4 v[230:233], v[76:77], off offset:512
	global_load_dwordx4 v[234:237], v[76:77], off offset:528
	s_mov_b32 s100, 0x20000
	s_mov_b32 s101, 0
	v_lshl_add_u64 v[242:243], v[76:77], 0, s[100:101]
	global_load_dwordx4 v[222:225], v[242:243], off
	global_load_dwordx4 v[226:229], v[242:243], off offset:16
	global_load_dwordx4 v[238:241], v[242:243], off offset:512
	global_load_dwordx4 v[242:245], v[242:243], off offset:528
	v_lshl_add_u64 v[74:75], v[74:75], 1, s[14:15]
	s_waitcnt vmcnt(7)
	v_pk_add_f32 v[62:63], v[62:63], v[68:69]
	v_pk_add_f32 v[60:61], v[60:61], v[66:67]
	s_waitcnt vmcnt(6)
	v_pk_add_f32 v[58:59], v[58:59], v[72:73]
	v_pk_add_f32 v[56:57], v[56:57], v[70:71]
	v_cvt_pk_bf16_f32 v66, v60, v61
	v_cvt_pk_bf16_f32 v67, v62, v63
	v_cvt_pk_bf16_f32 v68, v56, v57
	v_cvt_pk_bf16_f32 v69, v58, v59
	global_store_dwordx4 v[76:77], v[60:63], off
	global_store_dwordx4 v[76:77], v[56:59], off offset:16
	global_store_dwordx4 v[74:75], v[66:69], off
	v_mul_f32_e32 v61, v61, v61
	v_fmac_f32_e32 v61, v60, v60
	v_fmac_f32_e32 v61, v62, v62
	v_fmac_f32_e32 v61, v63, v63
	v_fmac_f32_e32 v61, v56, v56
	v_fmac_f32_e32 v61, v57, v57
	v_fmac_f32_e32 v61, v58, v58
	v_fmac_f32_e32 v61, v59, v59
	s_waitcnt vmcnt(8)
	v_pk_add_f32 v[54:55], v[54:55], v[232:233]
	v_pk_add_f32 v[52:53], v[52:53], v[230:231]
	s_waitcnt vmcnt(7)
	v_pk_add_f32 v[50:51], v[50:51], v[236:237]
	v_pk_add_f32 v[48:49], v[48:49], v[234:235]
	global_store_dwordx4 v[76:77], v[52:55], off offset:512
	global_store_dwordx4 v[76:77], v[48:51], off offset:528
	v_cvt_pk_bf16_f32 v56, v52, v53
	v_mul_f32_e32 v53, v53, v53
	v_fmac_f32_e32 v53, v52, v52
	v_fmac_f32_e32 v53, v54, v54
	v_fmac_f32_e32 v53, v55, v55
	v_fmac_f32_e32 v53, v48, v48
	v_fmac_f32_e32 v53, v49, v49
	v_fmac_f32_e32 v53, v50, v50
	v_fmac_f32_e32 v53, v51, v51
	v_add_f32_e32 v52, v61, v53
	ds_swizzle_b32 v53, v52 offset:swizzle(SWAP,16)
	v_cvt_pk_bf16_f32 v58, v48, v49
	v_cvt_pk_bf16_f32 v57, v54, v55
	v_cvt_pk_bf16_f32 v59, v50, v51
	global_store_dwordx4 v[74:75], v[56:59], off offset:256
	s_waitcnt lgkmcnt(0)
	v_add_f32_e32 v48, v52, v53
	v_mov_b32_e32 v49, v48
	s_nop 1
	v_permlane32_swap_b32_e32 v48, v49
	s_and_saveexec_b64 s[36:37], s[6:7]
	s_cbranch_execz .LBB0_1221
	v_add_f32_e32 v50, v48, v49
	v_lshlrev_b64 v[48:49], 7, v[64:65]
	v_lshl_add_u64 v[48:49], s[10:11], 0, v[48:49]
	v_lshl_add_u64 v[48:49], s[34:35], 2, v[48:49]
	s_lshl_b32 s20, s47, 2
	v_lshl_add_u64 v[48:49], v[48:49], 0, s[20:21]
	global_store_dword v[48:49], v50, off
.LBB0_1221:
	s_or_b64 exec, exec, s[36:37]
	v_add_u32_e32 v48, 0x90, v146
	v_ashrrev_i32_e32 v49, 31, v48
	v_lshlrev_b64 v[50:51], 11, v[48:49]
	v_lshl_add_u64 v[58:59], v[50:51], 0, v[144:145]
	v_lshl_add_u64 v[60:61], v[58:59], 2, s[16:17]
	v_lshl_add_u64 v[58:59], v[58:59], 1, s[14:15]
	s_waitcnt vmcnt(9)
	v_pk_add_f32 v[46:47], v[46:47], v[224:225]
	v_pk_add_f32 v[44:45], v[44:45], v[222:223]
	s_waitcnt vmcnt(8)
	v_pk_add_f32 v[42:43], v[42:43], v[228:229]
	v_pk_add_f32 v[40:41], v[40:41], v[226:227]
	v_cvt_pk_bf16_f32 v50, v44, v45
	v_cvt_pk_bf16_f32 v51, v46, v47
	v_cvt_pk_bf16_f32 v52, v40, v41
	v_cvt_pk_bf16_f32 v53, v42, v43
	global_store_dwordx4 v[60:61], v[44:47], off
	global_store_dwordx4 v[60:61], v[40:43], off offset:16
	global_store_dwordx4 v[58:59], v[50:53], off
	v_mul_f32_e32 v45, v45, v45
	v_fmac_f32_e32 v45, v44, v44
	v_fmac_f32_e32 v45, v46, v46
	v_fmac_f32_e32 v45, v47, v47
	v_fmac_f32_e32 v45, v40, v40
	v_fmac_f32_e32 v45, v41, v41
	v_fmac_f32_e32 v45, v42, v42
	v_fmac_f32_e32 v45, v43, v43
	s_waitcnt vmcnt(10)
	v_pk_add_f32 v[38:39], v[38:39], v[240:241]
	v_pk_add_f32 v[36:37], v[36:37], v[238:239]
	s_waitcnt vmcnt(9)
	v_pk_add_f32 v[34:35], v[34:35], v[244:245]
	v_pk_add_f32 v[32:33], v[32:33], v[242:243]
	global_store_dwordx4 v[60:61], v[36:39], off offset:512
	global_store_dwordx4 v[60:61], v[32:35], off offset:528
	v_cvt_pk_bf16_f32 v40, v36, v37
	v_mul_f32_e32 v37, v37, v37
	v_fmac_f32_e32 v37, v36, v36
	v_fmac_f32_e32 v37, v38, v38
	v_fmac_f32_e32 v37, v39, v39
	v_fmac_f32_e32 v37, v32, v32
	v_fmac_f32_e32 v37, v33, v33
	v_fmac_f32_e32 v37, v34, v34
	v_fmac_f32_e32 v37, v35, v35
	v_add_f32_e32 v36, v45, v37
	ds_swizzle_b32 v37, v36 offset:swizzle(SWAP,16)
	v_cvt_pk_bf16_f32 v42, v32, v33
	v_cvt_pk_bf16_f32 v41, v38, v39
	v_cvt_pk_bf16_f32 v43, v34, v35
	global_store_dwordx4 v[58:59], v[40:43], off offset:256
	s_waitcnt lgkmcnt(0)
	v_add_f32_e32 v32, v36, v37
	v_mov_b32_e32 v33, v32
	s_nop 1
	v_permlane32_swap_b32_e32 v32, v33
	s_and_saveexec_b64 s[36:37], s[6:7]
	s_cbranch_execz .LBB0_1223
	v_add_f32_e32 v34, v32, v33
	v_lshlrev_b64 v[32:33], 7, v[48:49]
	v_lshl_add_u64 v[32:33], s[10:11], 0, v[32:33]
	v_lshl_add_u64 v[32:33], s[34:35], 2, v[32:33]
	s_lshl_b32 s20, s47, 2
	v_lshl_add_u64 v[32:33], v[32:33], 0, s[20:21]
	global_store_dword v[32:33], v34, off
; __device__ __forceinline__ float swz16(float v) { return __builtin_bit_cast(float, __builtin_amdgcn_ds_swizzle(__builtin_bit_cast(int, v), 0x401F)); }
;     __device__ __forceinline__ void operator()(const f32x4 (&acc)[2][2][4][2], const Unit& u, int wr, int wc, int fr, int fq) const {
;     ...
;         for (int ai = 0; ai < 2; ++ai)
; #pragma unroll
;             for (int m = 0; m < 4; ++m) {
;                 const int row = row0 + ai * 128 + m * 16; float sq = 0.f;
; #pragma unroll
;                 for (int bj = 0; bj < 2; ++bj) {
;                     const size_t off = (size_t)row * DM + col0 + bj * 128;
;                     const f32x4 r0 = *(const f32x4*)(res + off), r1 = *(const f32x4*)(res + off + 4);
;                     const f32x4 v0 = acc[ai][bj][m][0] + r0, v1 = acc[ai][bj][m][1] + r1;
;                     *(f32x4*)(out + off) = v0; *(f32x4*)(out + off + 4) = v1;
;                     u32x4 o; o.x = pack2(v0[0], v0[1]); o.y = pack2(v0[2], v0[3]); o.z = pack2(v1[0], v1[1]); o.w = pack2(v1[2], v1[3]);
;                     *(u32x4*)(hb + off) = o;
;                     sq += v0[0] * v0[0] + v0[1] * v0[1] + v0[2] * v0[2] + v0[3] * v0[3] + v1[0] * v1[0] + v1[1] * v1[1] + v1[2] * v1[2] + v1[3] * v1[3];
;                 }
;                 sq += swz16(sq); sq = sum32(sq);
;                 if (fq == 0) ss_out[(size_t)row * 32 + u.pn * 4 + wc] = sq;
;             }
.LBB0_1223:
	s_or_b64 exec, exec, s[36:37]
	v_add_u32_e32 v32, 0xa0, v146
	v_ashrrev_i32_e32 v33, 31, v32
	v_lshlrev_b64 v[34:35], 11, v[32:33]
	v_lshl_add_u64 v[42:43], v[34:35], 0, v[144:145]
	v_lshl_add_u64 v[44:45], v[42:43], 2, s[16:17]
	global_load_dwordx4 v[34:37], v[44:45], off
	global_load_dwordx4 v[38:41], v[44:45], off offset:16
	global_load_dwordx4 v[230:233], v[44:45], off offset:512
	global_load_dwordx4 v[234:237], v[44:45], off offset:528
	s_mov_b32 s100, 0x20000
	s_mov_b32 s101, 0
	v_lshl_add_u64 v[242:243], v[44:45], 0, s[100:101]
	global_load_dwordx4 v[222:225], v[242:243], off
	global_load_dwordx4 v[226:229], v[242:243], off offset:16
	global_load_dwordx4 v[238:241], v[242:243], off offset:512
	global_load_dwordx4 v[242:245], v[242:243], off offset:528
	v_lshl_add_u64 v[42:43], v[42:43], 1, s[14:15]
	s_waitcnt vmcnt(7)
	v_pk_add_f32 v[30:31], v[30:31], v[36:37]
	v_pk_add_f32 v[28:29], v[28:29], v[34:35]
	s_waitcnt vmcnt(6)
	v_pk_add_f32 v[26:27], v[26:27], v[40:41]
	v_pk_add_f32 v[24:25], v[24:25], v[38:39]
	v_cvt_pk_bf16_f32 v34, v28, v29
	v_cvt_pk_bf16_f32 v35, v30, v31
	v_cvt_pk_bf16_f32 v36, v24, v25
	v_cvt_pk_bf16_f32 v37, v26, v27
	global_store_dwordx4 v[44:45], v[28:31], off
	global_store_dwordx4 v[44:45], v[24:27], off offset:16
	global_store_dwordx4 v[42:43], v[34:37], off
	v_mul_f32_e32 v29, v29, v29
	v_fmac_f32_e32 v29, v28, v28
	v_fmac_f32_e32 v29, v30, v30
	v_fmac_f32_e32 v29, v31, v31
	v_fmac_f32_e32 v29, v24, v24
	v_fmac_f32_e32 v29, v25, v25
	v_fmac_f32_e32 v29, v26, v26
	v_fmac_f32_e32 v29, v27, v27
	s_waitcnt vmcnt(8)
	v_pk_add_f32 v[22:23], v[22:23], v[232:233]
	v_pk_add_f32 v[20:21], v[20:21], v[230:231]
	s_waitcnt vmcnt(7)
	v_pk_add_f32 v[18:19], v[18:19], v[236:237]
	v_pk_add_f32 v[16:17], v[16:17], v[234:235]
	global_store_dwordx4 v[44:45], v[20:23], off offset:512
	global_store_dwordx4 v[44:45], v[16:19], off offset:528
	v_cvt_pk_bf16_f32 v24, v20, v21
	v_mul_f32_e32 v21, v21, v21
	v_fmac_f32_e32 v21, v20, v20
	v_fmac_f32_e32 v21, v22, v22
	v_fmac_f32_e32 v21, v23, v23
	v_fmac_f32_e32 v21, v16, v16
	v_fmac_f32_e32 v21, v17, v17
	v_fmac_f32_e32 v21, v18, v18
	v_fmac_f32_e32 v21, v19, v19
	v_add_f32_e32 v20, v29, v21
	ds_swizzle_b32 v21, v20 offset:swizzle(SWAP,16)
	v_cvt_pk_bf16_f32 v26, v16, v17
	v_cvt_pk_bf16_f32 v25, v22, v23
	v_cvt_pk_bf16_f32 v27, v18, v19
	global_store_dwordx4 v[42:43], v[24:27], off offset:256
	s_waitcnt lgkmcnt(0)
	v_add_f32_e32 v16, v20, v21
	v_mov_b32_e32 v17, v16
	s_nop 1
	v_permlane32_swap_b32_e32 v16, v17
	s_and_saveexec_b64 s[36:37], s[6:7]
	s_cbranch_execz .LBB0_1225
	v_add_f32_e32 v18, v16, v17
	v_lshlrev_b64 v[16:17], 7, v[32:33]
	v_lshl_add_u64 v[16:17], s[10:11], 0, v[16:17]
	v_lshl_add_u64 v[16:17], s[34:35], 2, v[16:17]
	s_lshl_b32 s20, s47, 2
	v_lshl_add_u64 v[16:17], v[16:17], 0, s[20:21]
	global_store_dword v[16:17], v18, off
.LBB0_1225:
	s_or_b64 exec, exec, s[36:37]
	v_add_u32_e32 v16, 0xb0, v146
	v_ashrrev_i32_e32 v17, 31, v16
	v_lshlrev_b64 v[18:19], 11, v[16:17]
	v_lshl_add_u64 v[26:27], v[18:19], 0, v[144:145]
	v_lshl_add_u64 v[28:29], v[26:27], 2, s[16:17]
	v_lshl_add_u64 v[26:27], v[26:27], 1, s[14:15]
	s_waitcnt vmcnt(9)
	v_pk_add_f32 v[14:15], v[14:15], v[224:225]
	v_pk_add_f32 v[12:13], v[12:13], v[222:223]
	s_waitcnt vmcnt(8)
	v_pk_add_f32 v[10:11], v[10:11], v[228:229]
	v_pk_add_f32 v[8:9], v[8:9], v[226:227]
	v_cvt_pk_bf16_f32 v18, v12, v13
	v_cvt_pk_bf16_f32 v19, v14, v15
	v_cvt_pk_bf16_f32 v20, v8, v9
	v_cvt_pk_bf16_f32 v21, v10, v11
	global_store_dwordx4 v[28:29], v[12:15], off
	global_store_dwordx4 v[28:29], v[8:11], off offset:16
	global_store_dwordx4 v[26:27], v[18:21], off
	v_mul_f32_e32 v13, v13, v13
	v_fmac_f32_e32 v13, v12, v12
	v_fmac_f32_e32 v13, v14, v14
	v_fmac_f32_e32 v13, v15, v15
	v_fmac_f32_e32 v13, v8, v8
	v_fmac_f32_e32 v13, v9, v9
	v_fmac_f32_e32 v13, v10, v10
	v_fmac_f32_e32 v13, v11, v11
	s_waitcnt vmcnt(10)
	v_pk_add_f32 v[6:7], v[6:7], v[240:241]
	v_pk_add_f32 v[4:5], v[4:5], v[238:239]
	s_waitcnt vmcnt(9)
	v_pk_add_f32 v[2:3], v[2:3], v[244:245]
	v_pk_add_f32 v[0:1], v[0:1], v[242:243]
	global_store_dwordx4 v[28:29], v[4:7], off offset:512
	global_store_dwordx4 v[28:29], v[0:3], off offset:528
	v_cvt_pk_bf16_f32 v8, v4, v5
	v_mul_f32_e32 v5, v5, v5
	v_fmac_f32_e32 v5, v4, v4
	v_fmac_f32_e32 v5, v6, v6
	v_fmac_f32_e32 v5, v7, v7
	v_fmac_f32_e32 v5, v0, v0
	v_fmac_f32_e32 v5, v1, v1
	v_fmac_f32_e32 v5, v2, v2
	v_fmac_f32_e32 v5, v3, v3
	v_add_f32_e32 v4, v13, v5
	ds_swizzle_b32 v5, v4 offset:swizzle(SWAP,16)
	v_cvt_pk_bf16_f32 v10, v0, v1
	v_cvt_pk_bf16_f32 v9, v6, v7
	v_cvt_pk_bf16_f32 v11, v2, v3
	global_store_dwordx4 v[26:27], v[8:11], off offset:256
	s_waitcnt lgkmcnt(0)
	v_add_f32_e32 v0, v4, v5
	v_mov_b32_e32 v1, v0
	s_nop 1
	v_permlane32_swap_b32_e32 v0, v1
	s_and_saveexec_b64 s[36:37], s[6:7]
	s_cbranch_execz .LBB0_1202
	v_add_f32_e32 v2, v0, v1
	v_lshlrev_b64 v[0:1], 7, v[16:17]
	v_lshl_add_u64 v[0:1], s[10:11], 0, v[0:1]
	v_lshl_add_u64 v[0:1], s[34:35], 2, v[0:1]
	s_lshl_b32 s20, s47, 2
	v_lshl_add_u64 v[0:1], v[0:1], 0, s[20:21]
	global_store_dword v[0:1], v2, off
	s_branch .LBB0_1202

; __device__ __forceinline__ float swz16(float v) { return __builtin_bit_cast(float, __builtin_amdgcn_ds_swizzle(__builtin_bit_cast(int, v), 0x401F)); }
;     __device__ __forceinline__ void operator()(const f32x4 (&acc)[2][2][4][2], const Unit& u, int wr, int wc, int fr, int fq) const {
;     ...
;         for (int ai = 0; ai < 2; ++ai)
; #pragma unroll
;             for (int m = 0; m < 4; ++m) {
;                 const int row = row0 + ai * 128 + m * 16; float sq = 0.f;
; #pragma unroll
;                 for (int bj = 0; bj < 2; ++bj) {
;                     const size_t off = (size_t)row * DM + col0 + bj * 128;
;                     const f32x4 r0 = *(const f32x4*)(res + off), r1 = *(const f32x4*)(res + off + 4);
;                     const f32x4 v0 = acc[ai][bj][m][0] + r0, v1 = acc[ai][bj][m][1] + r1;
;                     *(f32x4*)(out + off) = v0; *(f32x4*)(out + off + 4) = v1;
;                     u32x4 o; o.x = pack2(v0[0], v0[1]); o.y = pack2(v0[2], v0[3]); o.z = pack2(v1[0], v1[1]); o.w = pack2(v1[2], v1[3]);
;                     *(u32x4*)(hb + off) = o;
;                     sq += v0[0] * v0[0] + v0[1] * v0[1] + v0[2] * v0[2] + v0[3] * v0[3] + v1[0] * v1[0] + v1[1] * v1[1] + v1[2] * v1[2] + v1[3] * v1[3];
;                 }
;                 sq += swz16(sq); sq = sum32(sq);
;                 if (fq == 0) ss_out[(size_t)row * 32 + u.pn * 4 + wc] = sq;
;             }
.LBB0_1285:
	s_or_b64 exec, exec, s[36:37]
	v_or_b32_e32 v96, 32, v146
	v_ashrrev_i32_e32 v97, 31, v96
	v_lshlrev_b64 v[98:99], 11, v[96:97]
	v_lshl_add_u64 v[106:107], v[98:99], 0, v[144:145]
	v_lshl_add_u64 v[108:109], v[106:107], 2, s[12:13]
	global_load_dwordx4 v[98:101], v[108:109], off
	global_load_dwordx4 v[102:105], v[108:109], off offset:16
	global_load_dwordx4 v[230:233], v[108:109], off offset:512
	global_load_dwordx4 v[234:237], v[108:109], off offset:528
	s_mov_b32 s100, 0x20000
	s_mov_b32 s101, 0
	v_lshl_add_u64 v[242:243], v[108:109], 0, s[100:101]
	global_load_dwordx4 v[222:225], v[242:243], off
	global_load_dwordx4 v[226:229], v[242:243], off offset:16
	global_load_dwordx4 v[238:241], v[242:243], off offset:512
	global_load_dwordx4 v[242:245], v[242:243], off offset:528
	v_lshl_add_u64 v[106:107], v[106:107], 1, s[10:11]
	s_waitcnt vmcnt(7)
	v_pk_add_f32 v[94:95], v[94:95], v[100:101]
	v_pk_add_f32 v[92:93], v[92:93], v[98:99]
	s_waitcnt vmcnt(6)
	v_pk_add_f32 v[90:91], v[90:91], v[104:105]
	v_pk_add_f32 v[88:89], v[88:89], v[102:103]
	v_cvt_pk_bf16_f32 v98, v92, v93
	v_cvt_pk_bf16_f32 v99, v94, v95
	v_cvt_pk_bf16_f32 v100, v88, v89
	v_cvt_pk_bf16_f32 v101, v90, v91
	global_store_dwordx4 v[108:109], v[92:95], off
	global_store_dwordx4 v[108:109], v[88:91], off offset:16
	global_store_dwordx4 v[106:107], v[98:101], off
	v_mul_f32_e32 v93, v93, v93
	v_fmac_f32_e32 v93, v92, v92
	v_fmac_f32_e32 v93, v94, v94
	v_fmac_f32_e32 v93, v95, v95
	v_fmac_f32_e32 v93, v88, v88
	v_fmac_f32_e32 v93, v89, v89
	v_fmac_f32_e32 v93, v90, v90
	v_fmac_f32_e32 v93, v91, v91
	s_waitcnt vmcnt(8)
	v_pk_add_f32 v[86:87], v[86:87], v[232:233]
	v_pk_add_f32 v[84:85], v[84:85], v[230:231]
	s_waitcnt vmcnt(7)
	v_pk_add_f32 v[82:83], v[82:83], v[236:237]
	v_pk_add_f32 v[80:81], v[80:81], v[234:235]
	global_store_dwordx4 v[108:109], v[84:87], off offset:512
	global_store_dwordx4 v[108:109], v[80:83], off offset:528
	v_cvt_pk_bf16_f32 v88, v84, v85
	v_mul_f32_e32 v85, v85, v85
	v_fmac_f32_e32 v85, v84, v84
	v_fmac_f32_e32 v85, v86, v86
	v_fmac_f32_e32 v85, v87, v87
	v_fmac_f32_e32 v85, v80, v80
	v_fmac_f32_e32 v85, v81, v81
	v_fmac_f32_e32 v85, v82, v82
	v_fmac_f32_e32 v85, v83, v83
	v_add_f32_e32 v84, v93, v85
	ds_swizzle_b32 v85, v84 offset:swizzle(SWAP,16)
	v_cvt_pk_bf16_f32 v90, v80, v81
	v_cvt_pk_bf16_f32 v89, v86, v87
	v_cvt_pk_bf16_f32 v91, v82, v83
	global_store_dwordx4 v[106:107], v[88:91], off offset:256
	s_waitcnt lgkmcnt(0)
	v_add_f32_e32 v80, v84, v85
	v_mov_b32_e32 v81, v80
	s_nop 1
	v_permlane32_swap_b32_e32 v80, v81
	s_and_saveexec_b64 s[36:37], s[6:7]
	s_cbranch_execz .LBB0_1287
	v_add_f32_e32 v82, v80, v81
	v_lshlrev_b64 v[80:81], 7, v[96:97]
	v_lshl_add_u64 v[80:81], s[18:19], 0, v[80:81]
	v_lshl_add_u64 v[80:81], s[34:35], 2, v[80:81]
	s_lshl_b32 s20, s47, 2
	v_lshl_add_u64 v[80:81], v[80:81], 0, s[20:21]
	global_store_dword v[80:81], v82, off
.LBB0_1287:
	s_or_b64 exec, exec, s[36:37]
	v_or_b32_e32 v80, 48, v146
	v_ashrrev_i32_e32 v81, 31, v80
	v_lshlrev_b64 v[82:83], 11, v[80:81]
	v_lshl_add_u64 v[90:91], v[82:83], 0, v[144:145]
	v_lshl_add_u64 v[92:93], v[90:91], 2, s[12:13]
	v_lshl_add_u64 v[90:91], v[90:91], 1, s[10:11]
	s_waitcnt vmcnt(9)
	v_pk_add_f32 v[78:79], v[78:79], v[224:225]
	v_pk_add_f32 v[76:77], v[76:77], v[222:223]
	s_waitcnt vmcnt(8)
	v_pk_add_f32 v[74:75], v[74:75], v[228:229]
	v_pk_add_f32 v[72:73], v[72:73], v[226:227]
	v_cvt_pk_bf16_f32 v82, v76, v77
	v_cvt_pk_bf16_f32 v83, v78, v79
	v_cvt_pk_bf16_f32 v84, v72, v73
	v_cvt_pk_bf16_f32 v85, v74, v75
	global_store_dwordx4 v[92:93], v[76:79], off
	global_store_dwordx4 v[92:93], v[72:75], off offset:16
	global_store_dwordx4 v[90:91], v[82:85], off
	v_mul_f32_e32 v77, v77, v77
	v_fmac_f32_e32 v77, v76, v76
	v_fmac_f32_e32 v77, v78, v78
	v_fmac_f32_e32 v77, v79, v79
	v_fmac_f32_e32 v77, v72, v72
	v_fmac_f32_e32 v77, v73, v73
	v_fmac_f32_e32 v77, v74, v74
	v_fmac_f32_e32 v77, v75, v75
	s_waitcnt vmcnt(10)
	v_pk_add_f32 v[70:71], v[70:71], v[240:241]
	v_pk_add_f32 v[68:69], v[68:69], v[238:239]
	s_waitcnt vmcnt(9)
	v_pk_add_f32 v[66:67], v[66:67], v[244:245]
	v_pk_add_f32 v[64:65], v[64:65], v[242:243]
	global_store_dwordx4 v[92:93], v[68:71], off offset:512
	global_store_dwordx4 v[92:93], v[64:67], off offset:528
	v_cvt_pk_bf16_f32 v72, v68, v69
	v_mul_f32_e32 v69, v69, v69
	v_fmac_f32_e32 v69, v68, v68
	v_fmac_f32_e32 v69, v70, v70
	v_fmac_f32_e32 v69, v71, v71
	v_fmac_f32_e32 v69, v64, v64
	v_fmac_f32_e32 v69, v65, v65
	v_fmac_f32_e32 v69, v66, v66
	v_fmac_f32_e32 v69, v67, v67
	v_add_f32_e32 v68, v77, v69
	ds_swizzle_b32 v69, v68 offset:swizzle(SWAP,16)
	v_cvt_pk_bf16_f32 v74, v64, v65
	v_cvt_pk_bf16_f32 v73, v70, v71
	v_cvt_pk_bf16_f32 v75, v66, v67
	global_store_dwordx4 v[90:91], v[72:75], off offset:256
	s_waitcnt lgkmcnt(0)
	v_add_f32_e32 v64, v68, v69
	v_mov_b32_e32 v65, v64
	s_nop 1
	v_permlane32_swap_b32_e32 v64, v65
	s_and_saveexec_b64 s[36:37], s[6:7]
	s_cbranch_execz .LBB0_1289
	v_add_f32_e32 v66, v64, v65
	v_lshlrev_b64 v[64:65], 7, v[80:81]
	v_lshl_add_u64 v[64:65], s[18:19], 0, v[64:65]
	v_lshl_add_u64 v[64:65], s[34:35], 2, v[64:65]
	s_lshl_b32 s20, s47, 2
	v_lshl_add_u64 v[64:65], v[64:65], 0, s[20:21]
	global_store_dword v[64:65], v66, off
; __device__ __forceinline__ float swz16(float v) { return __builtin_bit_cast(float, __builtin_amdgcn_ds_swizzle(__builtin_bit_cast(int, v), 0x401F)); }
;     __device__ __forceinline__ void operator()(const f32x4 (&acc)[2][2][4][2], const Unit& u, int wr, int wc, int fr, int fq) const {
;     ...
;         for (int ai = 0; ai < 2; ++ai)
; #pragma unroll
;             for (int m = 0; m < 4; ++m) {
;                 const int row = row0 + ai * 128 + m * 16; float sq = 0.f;
; #pragma unroll
;                 for (int bj = 0; bj < 2; ++bj) {
;                     const size_t off = (size_t)row * DM + col0 + bj * 128;
;                     const f32x4 r0 = *(const f32x4*)(res + off), r1 = *(const f32x4*)(res + off + 4);
;                     const f32x4 v0 = acc[ai][bj][m][0] + r0, v1 = acc[ai][bj][m][1] + r1;
;                     *(f32x4*)(out + off) = v0; *(f32x4*)(out + off + 4) = v1;
;                     u32x4 o; o.x = pack2(v0[0], v0[1]); o.y = pack2(v0[2], v0[3]); o.z = pack2(v1[0], v1[1]); o.w = pack2(v1[2], v1[3]);
;                     *(u32x4*)(hb + off) = o;
;                     sq += v0[0] * v0[0] + v0[1] * v0[1] + v0[2] * v0[2] + v0[3] * v0[3] + v1[0] * v1[0] + v1[1] * v1[1] + v1[2] * v1[2] + v1[3] * v1[3];
;                 }
;                 sq += swz16(sq); sq = sum32(sq);
;                 if (fq == 0) ss_out[(size_t)row * 32 + u.pn * 4 + wc] = sq;
;             }
.LBB0_1289:
	s_or_b64 exec, exec, s[36:37]
	v_add_u32_e32 v64, 0x80, v146
	v_ashrrev_i32_e32 v65, 31, v64
	v_lshlrev_b64 v[66:67], 11, v[64:65]
	v_lshl_add_u64 v[74:75], v[66:67], 0, v[144:145]
	v_lshl_add_u64 v[76:77], v[74:75], 2, s[12:13]
	global_load_dwordx4 v[66:69], v[76:77], off
	global_load_dwordx4 v[70:73], v[76:77], off offset:16
	global_load_dwordx4 v[230:233], v[76:77], off offset:512
	global_load_dwordx4 v[234:237], v[76:77], off offset:528
	s_mov_b32 s100, 0x20000
	s_mov_b32 s101, 0
	v_lshl_add_u64 v[242:243], v[76:77], 0, s[100:101]
	global_load_dwordx4 v[222:225], v[242:243], off
	global_load_dwordx4 v[226:229], v[242:243], off offset:16
	global_load_dwordx4 v[238:241], v[242:243], off offset:512
	global_load_dwordx4 v[242:245], v[242:243], off offset:528
	v_lshl_add_u64 v[74:75], v[74:75], 1, s[10:11]
	s_waitcnt vmcnt(7)
	v_pk_add_f32 v[62:63], v[62:63], v[68:69]
	v_pk_add_f32 v[60:61], v[60:61], v[66:67]
	s_waitcnt vmcnt(6)
	v_pk_add_f32 v[58:59], v[58:59], v[72:73]
	v_pk_add_f32 v[56:57], v[56:57], v[70:71]
	v_cvt_pk_bf16_f32 v66, v60, v61
	v_cvt_pk_bf16_f32 v67, v62, v63
	v_cvt_pk_bf16_f32 v68, v56, v57
	v_cvt_pk_bf16_f32 v69, v58, v59
	global_store_dwordx4 v[76:77], v[60:63], off
	global_store_dwordx4 v[76:77], v[56:59], off offset:16
	global_store_dwordx4 v[74:75], v[66:69], off
	v_mul_f32_e32 v61, v61, v61
	v_fmac_f32_e32 v61, v60, v60
	v_fmac_f32_e32 v61, v62, v62
	v_fmac_f32_e32 v61, v63, v63
	v_fmac_f32_e32 v61, v56, v56
	v_fmac_f32_e32 v61, v57, v57
	v_fmac_f32_e32 v61, v58, v58
	v_fmac_f32_e32 v61, v59, v59
	s_waitcnt vmcnt(8)
	v_pk_add_f32 v[54:55], v[54:55], v[232:233]
	v_pk_add_f32 v[52:53], v[52:53], v[230:231]
	s_waitcnt vmcnt(7)
	v_pk_add_f32 v[50:51], v[50:51], v[236:237]
	v_pk_add_f32 v[48:49], v[48:49], v[234:235]
	global_store_dwordx4 v[76:77], v[52:55], off offset:512
	global_store_dwordx4 v[76:77], v[48:51], off offset:528
	v_cvt_pk_bf16_f32 v56, v52, v53
	v_mul_f32_e32 v53, v53, v53
	v_fmac_f32_e32 v53, v52, v52
	v_fmac_f32_e32 v53, v54, v54
	v_fmac_f32_e32 v53, v55, v55
	v_fmac_f32_e32 v53, v48, v48
	v_fmac_f32_e32 v53, v49, v49
	v_fmac_f32_e32 v53, v50, v50
	v_fmac_f32_e32 v53, v51, v51
	v_add_f32_e32 v52, v61, v53
	ds_swizzle_b32 v53, v52 offset:swizzle(SWAP,16)
	v_cvt_pk_bf16_f32 v58, v48, v49
	v_cvt_pk_bf16_f32 v57, v54, v55
	v_cvt_pk_bf16_f32 v59, v50, v51
	global_store_dwordx4 v[74:75], v[56:59], off offset:256
	s_waitcnt lgkmcnt(0)
	v_add_f32_e32 v48, v52, v53
	v_mov_b32_e32 v49, v48
	s_nop 1
	v_permlane32_swap_b32_e32 v48, v49
	s_and_saveexec_b64 s[36:37], s[6:7]
	s_cbranch_execz .LBB0_1291
	v_add_f32_e32 v50, v48, v49
	v_lshlrev_b64 v[48:49], 7, v[64:65]
	v_lshl_add_u64 v[48:49], s[18:19], 0, v[48:49]
	v_lshl_add_u64 v[48:49], s[34:35], 2, v[48:49]
	s_lshl_b32 s20, s47, 2
	v_lshl_add_u64 v[48:49], v[48:49], 0, s[20:21]
	global_store_dword v[48:49], v50, off
.LBB0_1291:
	s_or_b64 exec, exec, s[36:37]
	v_add_u32_e32 v48, 0x90, v146
	v_ashrrev_i32_e32 v49, 31, v48
	v_lshlrev_b64 v[50:51], 11, v[48:49]
	v_lshl_add_u64 v[58:59], v[50:51], 0, v[144:145]
	v_lshl_add_u64 v[60:61], v[58:59], 2, s[12:13]
	v_lshl_add_u64 v[58:59], v[58:59], 1, s[10:11]
	s_waitcnt vmcnt(9)
	v_pk_add_f32 v[46:47], v[46:47], v[224:225]
	v_pk_add_f32 v[44:45], v[44:45], v[222:223]
	s_waitcnt vmcnt(8)
	v_pk_add_f32 v[42:43], v[42:43], v[228:229]
	v_pk_add_f32 v[40:41], v[40:41], v[226:227]
	v_cvt_pk_bf16_f32 v50, v44, v45
	v_cvt_pk_bf16_f32 v51, v46, v47
	v_cvt_pk_bf16_f32 v52, v40, v41
	v_cvt_pk_bf16_f32 v53, v42, v43
	global_store_dwordx4 v[60:61], v[44:47], off
	global_store_dwordx4 v[60:61], v[40:43], off offset:16
	global_store_dwordx4 v[58:59], v[50:53], off
	v_mul_f32_e32 v45, v45, v45
	v_fmac_f32_e32 v45, v44, v44
	v_fmac_f32_e32 v45, v46, v46
	v_fmac_f32_e32 v45, v47, v47
	v_fmac_f32_e32 v45, v40, v40
	v_fmac_f32_e32 v45, v41, v41
	v_fmac_f32_e32 v45, v42, v42
	v_fmac_f32_e32 v45, v43, v43
	s_waitcnt vmcnt(10)
	v_pk_add_f32 v[38:39], v[38:39], v[240:241]
	v_pk_add_f32 v[36:37], v[36:37], v[238:239]
	s_waitcnt vmcnt(9)
	v_pk_add_f32 v[34:35], v[34:35], v[244:245]
	v_pk_add_f32 v[32:33], v[32:33], v[242:243]
	global_store_dwordx4 v[60:61], v[36:39], off offset:512
	global_store_dwordx4 v[60:61], v[32:35], off offset:528
	v_cvt_pk_bf16_f32 v40, v36, v37
	v_mul_f32_e32 v37, v37, v37
	v_fmac_f32_e32 v37, v36, v36
	v_fmac_f32_e32 v37, v38, v38
	v_fmac_f32_e32 v37, v39, v39
	v_fmac_f32_e32 v37, v32, v32
	v_fmac_f32_e32 v37, v33, v33
	v_fmac_f32_e32 v37, v34, v34
	v_fmac_f32_e32 v37, v35, v35
	v_add_f32_e32 v36, v45, v37
	ds_swizzle_b32 v37, v36 offset:swizzle(SWAP,16)
	v_cvt_pk_bf16_f32 v42, v32, v33
	v_cvt_pk_bf16_f32 v41, v38, v39
	v_cvt_pk_bf16_f32 v43, v34, v35
	global_store_dwordx4 v[58:59], v[40:43], off offset:256
	s_waitcnt lgkmcnt(0)
	v_add_f32_e32 v32, v36, v37
	v_mov_b32_e32 v33, v32
	s_nop 1
	v_permlane32_swap_b32_e32 v32, v33
	s_and_saveexec_b64 s[36:37], s[6:7]
	s_cbranch_execz .LBB0_1293
	v_add_f32_e32 v34, v32, v33
	v_lshlrev_b64 v[32:33], 7, v[48:49]
	v_lshl_add_u64 v[32:33], s[18:19], 0, v[32:33]
	v_lshl_add_u64 v[32:33], s[34:35], 2, v[32:33]
	s_lshl_b32 s20, s47, 2
	v_lshl_add_u64 v[32:33], v[32:33], 0, s[20:21]
	global_store_dword v[32:33], v34, off
; __device__ __forceinline__ float swz16(float v) { return __builtin_bit_cast(float, __builtin_amdgcn_ds_swizzle(__builtin_bit_cast(int, v), 0x401F)); }
;     __device__ __forceinline__ void operator()(const f32x4 (&acc)[2][2][4][2], const Unit& u, int wr, int wc, int fr, int fq) const {
;     ...
;         for (int ai = 0; ai < 2; ++ai)
; #pragma unroll
;             for (int m = 0; m < 4; ++m) {
;                 const int row = row0 + ai * 128 + m * 16; float sq = 0.f;
; #pragma unroll
;                 for (int bj = 0; bj < 2; ++bj) {
;                     const size_t off = (size_t)row * DM + col0 + bj * 128;
;                     const f32x4 r0 = *(const f32x4*)(res + off), r1 = *(const f32x4*)(res + off + 4);
;                     const f32x4 v0 = acc[ai][bj][m][0] + r0, v1 = acc[ai][bj][m][1] + r1;
;                     *(f32x4*)(out + off) = v0; *(f32x4*)(out + off + 4) = v1;
;                     u32x4 o; o.x = pack2(v0[0], v0[1]); o.y = pack2(v0[2], v0[3]); o.z = pack2(v1[0], v1[1]); o.w = pack2(v1[2], v1[3]);
;                     *(u32x4*)(hb + off) = o;
;                     sq += v0[0] * v0[0] + v0[1] * v0[1] + v0[2] * v0[2] + v0[3] * v0[3] + v1[0] * v1[0] + v1[1] * v1[1] + v1[2] * v1[2] + v1[3] * v1[3];
;                 }
;                 sq += swz16(sq); sq = sum32(sq);
;                 if (fq == 0) ss_out[(size_t)row * 32 + u.pn * 4 + wc] = sq;
;             }
.LBB0_1293:
	s_or_b64 exec, exec, s[36:37]
	v_add_u32_e32 v32, 0xa0, v146
	v_ashrrev_i32_e32 v33, 31, v32
	v_lshlrev_b64 v[34:35], 11, v[32:33]
	v_lshl_add_u64 v[42:43], v[34:35], 0, v[144:145]
	v_lshl_add_u64 v[44:45], v[42:43], 2, s[12:13]
	global_load_dwordx4 v[34:37], v[44:45], off
	global_load_dwordx4 v[38:41], v[44:45], off offset:16
	global_load_dwordx4 v[230:233], v[44:45], off offset:512
	global_load_dwordx4 v[234:237], v[44:45], off offset:528
	s_mov_b32 s100, 0x20000
	s_mov_b32 s101, 0
	v_lshl_add_u64 v[242:243], v[44:45], 0, s[100:101]
	global_load_dwordx4 v[222:225], v[242:243], off
	global_load_dwordx4 v[226:229], v[242:243], off offset:16
	global_load_dwordx4 v[238:241], v[242:243], off offset:512
	global_load_dwordx4 v[242:245], v[242:243], off offset:528
	v_lshl_add_u64 v[42:43], v[42:43], 1, s[10:11]
	s_waitcnt vmcnt(7)
	v_pk_add_f32 v[30:31], v[30:31], v[36:37]
	v_pk_add_f32 v[28:29], v[28:29], v[34:35]
	s_waitcnt vmcnt(6)
	v_pk_add_f32 v[26:27], v[26:27], v[40:41]
	v_pk_add_f32 v[24:25], v[24:25], v[38:39]
	v_cvt_pk_bf16_f32 v34, v28, v29
	v_cvt_pk_bf16_f32 v35, v30, v31
	v_cvt_pk_bf16_f32 v36, v24, v25
	v_cvt_pk_bf16_f32 v37, v26, v27
	global_store_dwordx4 v[44:45], v[28:31], off
	global_store_dwordx4 v[44:45], v[24:27], off offset:16
	global_store_dwordx4 v[42:43], v[34:37], off
	v_mul_f32_e32 v29, v29, v29
	v_fmac_f32_e32 v29, v28, v28
	v_fmac_f32_e32 v29, v30, v30
	v_fmac_f32_e32 v29, v31, v31
	v_fmac_f32_e32 v29, v24, v24
	v_fmac_f32_e32 v29, v25, v25
	v_fmac_f32_e32 v29, v26, v26
	v_fmac_f32_e32 v29, v27, v27
	s_waitcnt vmcnt(8)
	v_pk_add_f32 v[22:23], v[22:23], v[232:233]
	v_pk_add_f32 v[20:21], v[20:21], v[230:231]
	s_waitcnt vmcnt(7)
	v_pk_add_f32 v[18:19], v[18:19], v[236:237]
	v_pk_add_f32 v[16:17], v[16:17], v[234:235]
	global_store_dwordx4 v[44:45], v[20:23], off offset:512
	global_store_dwordx4 v[44:45], v[16:19], off offset:528
	v_cvt_pk_bf16_f32 v24, v20, v21
	v_mul_f32_e32 v21, v21, v21
	v_fmac_f32_e32 v21, v20, v20
	v_fmac_f32_e32 v21, v22, v22
	v_fmac_f32_e32 v21, v23, v23
	v_fmac_f32_e32 v21, v16, v16
	v_fmac_f32_e32 v21, v17, v17
	v_fmac_f32_e32 v21, v18, v18
	v_fmac_f32_e32 v21, v19, v19
	v_add_f32_e32 v20, v29, v21
	ds_swizzle_b32 v21, v20 offset:swizzle(SWAP,16)
	v_cvt_pk_bf16_f32 v26, v16, v17
	v_cvt_pk_bf16_f32 v25, v22, v23
	v_cvt_pk_bf16_f32 v27, v18, v19
	global_store_dwordx4 v[42:43], v[24:27], off offset:256
	s_waitcnt lgkmcnt(0)
	v_add_f32_e32 v16, v20, v21
	v_mov_b32_e32 v17, v16
	s_nop 1
	v_permlane32_swap_b32_e32 v16, v17
	s_and_saveexec_b64 s[36:37], s[6:7]
	s_cbranch_execz .LBB0_1295
	v_add_f32_e32 v18, v16, v17
	v_lshlrev_b64 v[16:17], 7, v[32:33]
	v_lshl_add_u64 v[16:17], s[18:19], 0, v[16:17]
	v_lshl_add_u64 v[16:17], s[34:35], 2, v[16:17]
	s_lshl_b32 s20, s47, 2
	v_lshl_add_u64 v[16:17], v[16:17], 0, s[20:21]
	global_store_dword v[16:17], v18, off
.LBB0_1295:
	s_or_b64 exec, exec, s[36:37]
	v_add_u32_e32 v16, 0xb0, v146
	v_ashrrev_i32_e32 v17, 31, v16
	v_lshlrev_b64 v[18:19], 11, v[16:17]
	v_lshl_add_u64 v[26:27], v[18:19], 0, v[144:145]
	v_lshl_add_u64 v[28:29], v[26:27], 2, s[12:13]
	v_lshl_add_u64 v[26:27], v[26:27], 1, s[10:11]
	s_waitcnt vmcnt(9)
	v_pk_add_f32 v[14:15], v[14:15], v[224:225]
	v_pk_add_f32 v[12:13], v[12:13], v[222:223]
	s_waitcnt vmcnt(8)
	v_pk_add_f32 v[10:11], v[10:11], v[228:229]
	v_pk_add_f32 v[8:9], v[8:9], v[226:227]
	v_cvt_pk_bf16_f32 v18, v12, v13
	v_cvt_pk_bf16_f32 v19, v14, v15
	v_cvt_pk_bf16_f32 v20, v8, v9
	v_cvt_pk_bf16_f32 v21, v10, v11
	global_store_dwordx4 v[28:29], v[12:15], off
	global_store_dwordx4 v[28:29], v[8:11], off offset:16
	global_store_dwordx4 v[26:27], v[18:21], off
	v_mul_f32_e32 v13, v13, v13
	v_fmac_f32_e32 v13, v12, v12
	v_fmac_f32_e32 v13, v14, v14
	v_fmac_f32_e32 v13, v15, v15
	v_fmac_f32_e32 v13, v8, v8
	v_fmac_f32_e32 v13, v9, v9
	v_fmac_f32_e32 v13, v10, v10
	v_fmac_f32_e32 v13, v11, v11
	s_waitcnt vmcnt(10)
	v_pk_add_f32 v[6:7], v[6:7], v[240:241]
	v_pk_add_f32 v[4:5], v[4:5], v[238:239]
	s_waitcnt vmcnt(9)
	v_pk_add_f32 v[2:3], v[2:3], v[244:245]
	v_pk_add_f32 v[0:1], v[0:1], v[242:243]
	global_store_dwordx4 v[28:29], v[4:7], off offset:512
	global_store_dwordx4 v[28:29], v[0:3], off offset:528
	v_cvt_pk_bf16_f32 v8, v4, v5
	v_mul_f32_e32 v5, v5, v5
	v_fmac_f32_e32 v5, v4, v4
	v_fmac_f32_e32 v5, v6, v6
	v_fmac_f32_e32 v5, v7, v7
	v_fmac_f32_e32 v5, v0, v0
	v_fmac_f32_e32 v5, v1, v1
	v_fmac_f32_e32 v5, v2, v2
	v_fmac_f32_e32 v5, v3, v3
	v_add_f32_e32 v4, v13, v5
	ds_swizzle_b32 v5, v4 offset:swizzle(SWAP,16)
	v_cvt_pk_bf16_f32 v10, v0, v1
	v_cvt_pk_bf16_f32 v9, v6, v7
	v_cvt_pk_bf16_f32 v11, v2, v3
	global_store_dwordx4 v[26:27], v[8:11], off offset:256
	s_waitcnt lgkmcnt(0)
	v_add_f32_e32 v0, v4, v5
	v_mov_b32_e32 v1, v0
	s_nop 1
	v_permlane32_swap_b32_e32 v0, v1
	s_and_saveexec_b64 s[36:37], s[6:7]
	s_cbranch_execz .LBB0_1272
	v_add_f32_e32 v2, v0, v1
	v_lshlrev_b64 v[0:1], 7, v[16:17]
	v_lshl_add_u64 v[0:1], s[18:19], 0, v[0:1]
	v_lshl_add_u64 v[0:1], s[34:35], 2, v[0:1]
	s_lshl_b32 s20, s47, 2
	v_lshl_add_u64 v[0:1], v[0:1], 0, s[20:21]
	global_store_dword v[0:1], v2, off
	s_branch .LBB0_1272

; #define LAS __attribute__((address_space(3)))
; #define MK_PH(L, S, K) run_phase<L>(wv, S, lds); grid_barrier(wv, K);
; __global__ __launch_bounds__(512, 2) void mk_forward(Params p_) {
;     extern __shared__ __attribute__((aligned(16))) unsigned char shm[];
;     LAS unsigned char* lds = (LAS unsigned char*)shm;
;     const int wv = __builtin_amdgcn_readfirstlane((int)(threadIdx.x >> 6));
;     if (gridDim.x == 0x7fffffffu) cg::this_grid().sync();
;     MK_PH(0, 0, 1) MK_PH(0, 1, 2) MK_PH(0, 2, 3) MK_PH(0, 3, 4) MK_PH(0, 4, 5) MK_PH(0, 5, 6) MK_PH(0, 6, 7) MK_PH(0, 7, 8) MK_PH(0, 8, 9)
;     MK_PH(1, 0, 10) MK_PH(1, 1, 11) MK_PH(1, 2, 12) MK_PH(1, 3, 13) MK_PH(1, 4, 14) MK_PH(1, 5, 15) MK_PH(1, 6, 16) MK_PH(1, 7, 17)
;     run_phase<1>(wv, 8, lds);
; }
	.amdhsa_kernel _Z10mk_forward6Params
		.amdhsa_group_segment_fixed_size 0
		.amdhsa_private_segment_fixed_size 0
		.amdhsa_kernarg_size 728
		.amdhsa_user_sgpr_count 2
		.amdhsa_user_sgpr_dispatch_ptr 0
		.amdhsa_user_sgpr_queue_ptr 0
		.amdhsa_user_sgpr_kernarg_segment_ptr 1
		.amdhsa_user_sgpr_dispatch_id 0
		.amdhsa_user_sgpr_kernarg_preload_length 0
		.amdhsa_user_sgpr_kernarg_preload_offset 0
		.amdhsa_user_sgpr_private_segment_size 0
		.amdhsa_uses_dynamic_stack 0
		.amdhsa_enable_private_segment 0
		.amdhsa_system_sgpr_workgroup_id_x 1
		.amdhsa_system_sgpr_workgroup_id_y 0
		.amdhsa_system_sgpr_workgroup_id_z 0
		.amdhsa_system_sgpr_workgroup_info 0
		.amdhsa_system_vgpr_workitem_id 2
		.amdhsa_next_free_vgpr 247
		.amdhsa_next_free_sgpr 102
		.amdhsa_accum_offset 248
		.amdhsa_reserve_vcc 1
		.amdhsa_float_round_mode_32 0
		.amdhsa_float_round_mode_16_64 0
		.amdhsa_float_denorm_mode_32 3
		.amdhsa_float_denorm_mode_16_64 3
		.amdhsa_dx10_clamp 1
		.amdhsa_ieee_mode 1
		.amdhsa_fp16_overflow 0
		.amdhsa_tg_split 0
		.amdhsa_exception_fp_ieee_invalid_op 0
		.amdhsa_exception_fp_denorm_src 0
		.amdhsa_exception_fp_ieee_div_zero 0
		.amdhsa_exception_fp_ieee_overflow 0
		.amdhsa_exception_fp_ieee_underflow 0
		.amdhsa_exception_fp_ieee_inexact 0
		.amdhsa_exception_int_div_zero 0
	.end_amdhsa_kernel

; #define LAS __attribute__((address_space(3)))
; #define MK_PH(L, S, K) run_phase<L>(wv, S, lds); grid_barrier(wv, K);
; __global__ __launch_bounds__(512, 2) void mk_forward(Params p_) {
;     extern __shared__ __attribute__((aligned(16))) unsigned char shm[];
;     LAS unsigned char* lds = (LAS unsigned char*)shm;
;     const int wv = __builtin_amdgcn_readfirstlane((int)(threadIdx.x >> 6));
;     if (gridDim.x == 0x7fffffffu) cg::this_grid().sync();
;     MK_PH(0, 0, 1) MK_PH(0, 1, 2) MK_PH(0, 2, 3) MK_PH(0, 3, 4) MK_PH(0, 4, 5) MK_PH(0, 5, 6) MK_PH(0, 6, 7) MK_PH(0, 7, 8) MK_PH(0, 8, 9)
;     MK_PH(1, 0, 10) MK_PH(1, 1, 11) MK_PH(1, 2, 12) MK_PH(1, 3, 13) MK_PH(1, 4, 14) MK_PH(1, 5, 15) MK_PH(1, 6, 16) MK_PH(1, 7, 17)
;     run_phase<1>(wv, 8, lds);
; }
amdhsa.kernels:
  - .agpr_count:     0
    .args:
      - .offset:         0
        .size:           472
        .value_kind:     by_value
      - .offset:         472
        .size:           4
        .value_kind:     hidden_block_count_x
      - .offset:         476
        .size:           4
        .value_kind:     hidden_block_count_y
      - .offset:         480
        .size:           4
        .value_kind:     hidden_block_count_z
      - .offset:         484
        .size:           2
        .value_kind:     hidden_group_size_x
      - .offset:         486
        .size:           2
        .value_kind:     hidden_group_size_y
      - .offset:         488
        .size:           2
        .value_kind:     hidden_group_size_z
      - .offset:         490
        .size:           2
        .value_kind:     hidden_remainder_x
      - .offset:         492
        .size:           2
        .value_kind:     hidden_remainder_y
      - .offset:         494
        .size:           2
        .value_kind:     hidden_remainder_z
      - .offset:         512
        .size:           8
        .value_kind:     hidden_global_offset_x
      - .offset:         520
        .size:           8
        .value_kind:     hidden_global_offset_y
      - .offset:         528
        .size:           8
        .value_kind:     hidden_global_offset_z
      - .offset:         536
        .size:           2
        .value_kind:     hidden_grid_dims
      - .offset:         560
        .size:           8
        .value_kind:     hidden_multigrid_sync_arg
      - .offset:         592
        .size:           4
        .value_kind:     hidden_dynamic_lds_size
    .group_segment_fixed_size: 0
    .kernarg_segment_align: 8
    .kernarg_segment_size: 728
    .language:       OpenCL C
    .language_version:
      - 2
      - 0
    .max_flat_workgroup_size: 512
    .name:           _Z10mk_forward6Params
    .private_segment_fixed_size: 0
    .sgpr_count:     108
    .sgpr_spill_count: 16
    .symbol:         _Z10mk_forward6Params.kd
    .uniform_work_group_size: 1
    .uses_dynamic_stack: false
    .vgpr_count:     247
    .vgpr_spill_count: 0
    .wavefront_size: 64
